# GEMM K-loops: LDS-DMA in SGPR-base + 32-bit VGPR offset form, removing 16 v_lshl_add_u64 per iteration from the loader waves
# speedup vs baseline: 1.0003x; 1.0003x over previous
.LBB0_217:
	s_add_u32 s36, s34, 0xfffc0080
	s_addc_u32 s37, s35, -1
	s_cmp_eq_u32 s71, 12
	s_cselect_b32 s39, s7, s37
	s_cselect_b32 s38, s25, s36
	s_cselect_b32 s37, s23, s70
	s_cselect_b32 s36, s68, s69
	s_add_u32 s98, s36, s12
	s_addc_u32 s99, s37, s13
	s_add_u32 s100, s38, s12
	s_addc_u32 s101, s39, s13
	s_add_i32 m0, s31, 0xc000
	s_nop 0
	global_load_lds_dwordx4 v138, s[34:35]
	s_add_i32 m0, s31, 0xe000
	s_nop 0
	global_load_lds_dwordx4 v140, s[34:35]
	ds_read_b128 v[146:149], v155
	ds_read_b128 v[158:161], v155 offset:1024
	ds_read_b128 v[162:165], v155 offset:2048
	ds_read_b128 v[166:169], v155 offset:3072
	ds_read_b128 v[170:173], v156
	ds_read_b128 v[174:177], v156 offset:1024
	ds_read_b128 v[178:181], v156 offset:2048
	ds_read_b128 v[182:185], v156 offset:3072
	ds_read_b128 v[186:189], v157
	ds_read_b128 v[190:193], v157 offset:1024
	ds_read_b128 v[194:197], v157 offset:2048
	ds_read_b128 v[198:201], v157 offset:3072
	ds_read_b128 v[202:205], v157 offset:4096
	ds_read_b128 v[206:209], v157 offset:5120
	ds_read_b128 v[210:213], v157 offset:6144
	ds_read_b128 v[214:217], v157 offset:7168
	s_waitcnt vmcnt(8)
	s_waitcnt lgkmcnt(0)
	s_setprio 1
	s_barrier
	v_mfma_f32_16x16x32_bf16 v[124:127], v[146:149], v[186:189], v[124:127]
	v_mfma_f32_16x16x32_bf16 v[120:123], v[162:165], v[186:189], v[120:123]
	v_mfma_f32_16x16x32_bf16 v[108:111], v[146:149], v[194:197], v[108:111]
	v_mfma_f32_16x16x32_bf16 v[104:107], v[162:165], v[194:197], v[104:107]
	v_mfma_f32_16x16x32_bf16 v[92:95], v[146:149], v[202:205], v[92:95]
	v_mfma_f32_16x16x32_bf16 v[88:91], v[162:165], v[202:205], v[88:91]
	v_mfma_f32_16x16x32_bf16 v[76:79], v[146:149], v[210:213], v[76:79]
	v_mfma_f32_16x16x32_bf16 v[72:75], v[162:165], v[210:213], v[72:75]
	v_mfma_f32_16x16x32_bf16 v[124:127], v[158:161], v[190:193], v[124:127]
	v_mfma_f32_16x16x32_bf16 v[120:123], v[166:169], v[190:193], v[120:123]
	v_mfma_f32_16x16x32_bf16 v[108:111], v[158:161], v[198:201], v[108:111]
	v_mfma_f32_16x16x32_bf16 v[104:107], v[166:169], v[198:201], v[104:107]
	v_mfma_f32_16x16x32_bf16 v[92:95], v[158:161], v[206:209], v[92:95]
	v_mfma_f32_16x16x32_bf16 v[88:91], v[166:169], v[206:209], v[88:91]
	v_mfma_f32_16x16x32_bf16 v[76:79], v[158:161], v[214:217], v[76:79]
	v_mfma_f32_16x16x32_bf16 v[72:75], v[166:169], v[214:217], v[72:75]
	s_setprio 0
	s_setprio 1
	v_mfma_f32_16x16x32_bf16 v[116:119], v[170:173], v[186:189], v[116:119]
	v_mfma_f32_16x16x32_bf16 v[112:115], v[178:181], v[186:189], v[112:115]
	v_mfma_f32_16x16x32_bf16 v[100:103], v[170:173], v[194:197], v[100:103]
	v_mfma_f32_16x16x32_bf16 v[96:99], v[178:181], v[194:197], v[96:99]
	v_mfma_f32_16x16x32_bf16 v[84:87], v[170:173], v[202:205], v[84:87]
	v_mfma_f32_16x16x32_bf16 v[80:83], v[178:181], v[202:205], v[80:83]
	v_mfma_f32_16x16x32_bf16 v[68:71], v[170:173], v[210:213], v[68:71]
	v_mfma_f32_16x16x32_bf16 v[64:67], v[178:181], v[210:213], v[64:67]
	v_mfma_f32_16x16x32_bf16 v[116:119], v[174:177], v[190:193], v[116:119]
	v_mfma_f32_16x16x32_bf16 v[112:115], v[182:185], v[190:193], v[112:115]
	v_mfma_f32_16x16x32_bf16 v[100:103], v[174:177], v[198:201], v[100:103]
	v_mfma_f32_16x16x32_bf16 v[96:99], v[182:185], v[198:201], v[96:99]
	v_mfma_f32_16x16x32_bf16 v[84:87], v[174:177], v[206:209], v[84:87]
	v_mfma_f32_16x16x32_bf16 v[80:83], v[182:185], v[206:209], v[80:83]
	v_mfma_f32_16x16x32_bf16 v[68:71], v[174:177], v[214:217], v[68:71]
	v_mfma_f32_16x16x32_bf16 v[64:67], v[182:185], v[214:217], v[64:67]
	s_barrier
	s_setprio 0
	s_add_i32 s72, s65, s43
	s_mov_b32 m0, s72
	s_nop 0
	global_load_lds_dwordx4 v130, s[36:37]
	s_add_i32 m0, s72, 0x2000
	s_add_u32 s72, s36, 0x40000
	s_addc_u32 s73, s37, 0
	s_add_i32 s74, s67, s43
	global_load_lds_dwordx4 v134, s[36:37]
	s_mov_b32 m0, s74
	s_nop 0
	global_load_lds_dwordx4 v130, s[72:73]
	s_add_i32 m0, s74, 0x2000
	s_nop 0
	global_load_lds_dwordx4 v134, s[72:73]
	s_mov_b32 m0, s31
	s_nop 0
	global_load_lds_dwordx4 v128, s[38:39]
	s_mov_b32 m0, s46
	s_nop 0
	global_load_lds_dwordx4 v132, s[38:39]
	ds_read_b128 v[186:189], v157 offset:16384
	ds_read_b128 v[190:193], v157 offset:17408
	ds_read_b128 v[194:197], v157 offset:18432
	ds_read_b128 v[198:201], v157 offset:19456
	ds_read_b128 v[202:205], v157 offset:20480
	ds_read_b128 v[206:209], v157 offset:21504
	ds_read_b128 v[210:213], v157 offset:22528
	ds_read_b128 v[214:217], v157 offset:23552
	s_waitcnt vmcnt(8)
	s_waitcnt lgkmcnt(0)
	s_setprio 1
	s_barrier
	v_mfma_f32_16x16x32_bf16 v[60:63], v[146:149], v[186:189], v[60:63]
	v_mfma_f32_16x16x32_bf16 v[56:59], v[162:165], v[186:189], v[56:59]
	v_mfma_f32_16x16x32_bf16 v[44:47], v[146:149], v[194:197], v[44:47]
	v_mfma_f32_16x16x32_bf16 v[40:43], v[162:165], v[194:197], v[40:43]
	v_mfma_f32_16x16x32_bf16 v[28:31], v[146:149], v[202:205], v[28:31]
	v_mfma_f32_16x16x32_bf16 v[24:27], v[162:165], v[202:205], v[24:27]
	v_mfma_f32_16x16x32_bf16 v[12:15], v[146:149], v[210:213], v[12:15]
	v_mfma_f32_16x16x32_bf16 v[8:11], v[162:165], v[210:213], v[8:11]
	v_mfma_f32_16x16x32_bf16 v[60:63], v[158:161], v[190:193], v[60:63]
	v_mfma_f32_16x16x32_bf16 v[56:59], v[166:169], v[190:193], v[56:59]
	v_mfma_f32_16x16x32_bf16 v[44:47], v[158:161], v[198:201], v[44:47]
	v_mfma_f32_16x16x32_bf16 v[40:43], v[166:169], v[198:201], v[40:43]
	v_mfma_f32_16x16x32_bf16 v[28:31], v[158:161], v[206:209], v[28:31]
	v_mfma_f32_16x16x32_bf16 v[24:27], v[166:169], v[206:209], v[24:27]
	v_mfma_f32_16x16x32_bf16 v[12:15], v[158:161], v[214:217], v[12:15]
	v_mfma_f32_16x16x32_bf16 v[8:11], v[166:169], v[214:217], v[8:11]
	s_setprio 0
	s_setprio 1
	v_mfma_f32_16x16x32_bf16 v[52:55], v[170:173], v[186:189], v[52:55]
	v_mfma_f32_16x16x32_bf16 v[48:51], v[178:181], v[186:189], v[48:51]
	v_mfma_f32_16x16x32_bf16 v[36:39], v[170:173], v[194:197], v[36:39]
	v_mfma_f32_16x16x32_bf16 v[32:35], v[178:181], v[194:197], v[32:35]
	v_mfma_f32_16x16x32_bf16 v[20:23], v[170:173], v[202:205], v[20:23]
	v_mfma_f32_16x16x32_bf16 v[16:19], v[178:181], v[202:205], v[16:19]
	v_mfma_f32_16x16x32_bf16 v[4:7], v[170:173], v[210:213], v[4:7]
	v_mfma_f32_16x16x32_bf16 v[0:3], v[178:181], v[210:213], v[0:3]
	v_mfma_f32_16x16x32_bf16 v[52:55], v[174:177], v[190:193], v[52:55]
	v_mfma_f32_16x16x32_bf16 v[48:51], v[182:185], v[190:193], v[48:51]
	v_mfma_f32_16x16x32_bf16 v[36:39], v[174:177], v[198:201], v[36:39]
	v_mfma_f32_16x16x32_bf16 v[32:35], v[182:185], v[198:201], v[32:35]
	v_mfma_f32_16x16x32_bf16 v[20:23], v[174:177], v[206:209], v[20:23]
	v_mfma_f32_16x16x32_bf16 v[16:19], v[182:185], v[206:209], v[16:19]
	v_mfma_f32_16x16x32_bf16 v[4:7], v[174:177], v[214:217], v[4:7]
	v_mfma_f32_16x16x32_bf16 v[0:3], v[182:185], v[214:217], v[0:3]
	s_barrier
	s_setprio 0
	s_add_i32 s72, 0, 0x18000
	s_add_i32 s73, 0, 0x1c000
	s_add_u32 s38, s38, 0x40000
	s_addc_u32 s39, s39, 0
	s_mov_b32 m0, s47
	s_nop 0
	global_load_lds_dwordx4 v128, s[38:39]
	s_mov_b32 m0, s48
	s_nop 0
	global_load_lds_dwordx4 v132, s[38:39]
	v_add_u32_e32 v136, s72, v153
	ds_read_b128 v[146:149], v136
	ds_read_b128 v[158:161], v136 offset:1024
	ds_read_b128 v[162:165], v136 offset:2048
	ds_read_b128 v[166:169], v136 offset:3072
	v_add_u32_e32 v136, s73, v153
	ds_read_b128 v[170:173], v136
	ds_read_b128 v[174:177], v136 offset:1024
	ds_read_b128 v[178:181], v136 offset:2048
	ds_read_b128 v[182:185], v136 offset:3072
	ds_read_b128 v[186:189], v157 offset:32768
	ds_read_b128 v[190:193], v157 offset:33792
	ds_read_b128 v[194:197], v157 offset:34816
	ds_read_b128 v[198:201], v157 offset:35840
	ds_read_b128 v[202:205], v157 offset:36864
	ds_read_b128 v[206:209], v157 offset:37888
	ds_read_b128 v[210:213], v157 offset:38912
	ds_read_b128 v[214:217], v157 offset:39936
	s_waitcnt vmcnt(8)
	s_waitcnt lgkmcnt(0)
	s_setprio 1
	s_barrier
	v_mfma_f32_16x16x32_bf16 v[124:127], v[146:149], v[186:189], v[124:127]
	v_mfma_f32_16x16x32_bf16 v[120:123], v[162:165], v[186:189], v[120:123]
	v_mfma_f32_16x16x32_bf16 v[108:111], v[146:149], v[194:197], v[108:111]
	v_mfma_f32_16x16x32_bf16 v[104:107], v[162:165], v[194:197], v[104:107]
	v_mfma_f32_16x16x32_bf16 v[92:95], v[146:149], v[202:205], v[92:95]
	v_mfma_f32_16x16x32_bf16 v[88:91], v[162:165], v[202:205], v[88:91]
	v_mfma_f32_16x16x32_bf16 v[76:79], v[146:149], v[210:213], v[76:79]
	v_mfma_f32_16x16x32_bf16 v[72:75], v[162:165], v[210:213], v[72:75]
	v_mfma_f32_16x16x32_bf16 v[124:127], v[158:161], v[190:193], v[124:127]
	v_mfma_f32_16x16x32_bf16 v[120:123], v[166:169], v[190:193], v[120:123]
	v_mfma_f32_16x16x32_bf16 v[108:111], v[158:161], v[198:201], v[108:111]
	v_mfma_f32_16x16x32_bf16 v[104:107], v[166:169], v[198:201], v[104:107]
	v_mfma_f32_16x16x32_bf16 v[92:95], v[158:161], v[206:209], v[92:95]
	v_mfma_f32_16x16x32_bf16 v[88:91], v[166:169], v[206:209], v[88:91]
	v_mfma_f32_16x16x32_bf16 v[76:79], v[158:161], v[214:217], v[76:79]
	v_mfma_f32_16x16x32_bf16 v[72:75], v[166:169], v[214:217], v[72:75]
	s_setprio 0
	s_setprio 1
	v_mfma_f32_16x16x32_bf16 v[116:119], v[170:173], v[186:189], v[116:119]
	v_mfma_f32_16x16x32_bf16 v[112:115], v[178:181], v[186:189], v[112:115]
	v_mfma_f32_16x16x32_bf16 v[100:103], v[170:173], v[194:197], v[100:103]
	v_mfma_f32_16x16x32_bf16 v[96:99], v[178:181], v[194:197], v[96:99]
	v_mfma_f32_16x16x32_bf16 v[84:87], v[170:173], v[202:205], v[84:87]
	v_mfma_f32_16x16x32_bf16 v[80:83], v[178:181], v[202:205], v[80:83]
	v_mfma_f32_16x16x32_bf16 v[68:71], v[170:173], v[210:213], v[68:71]
	v_mfma_f32_16x16x32_bf16 v[64:67], v[178:181], v[210:213], v[64:67]
	v_mfma_f32_16x16x32_bf16 v[116:119], v[174:177], v[190:193], v[116:119]
	v_mfma_f32_16x16x32_bf16 v[112:115], v[182:185], v[190:193], v[112:115]
	v_mfma_f32_16x16x32_bf16 v[100:103], v[174:177], v[198:201], v[100:103]
	v_mfma_f32_16x16x32_bf16 v[96:99], v[182:185], v[198:201], v[96:99]
	v_mfma_f32_16x16x32_bf16 v[84:87], v[174:177], v[206:209], v[84:87]
	v_mfma_f32_16x16x32_bf16 v[80:83], v[182:185], v[206:209], v[80:83]
	v_mfma_f32_16x16x32_bf16 v[68:71], v[174:177], v[214:217], v[68:71]
	v_mfma_f32_16x16x32_bf16 v[64:67], v[182:185], v[214:217], v[64:67]
	s_barrier
	s_setprio 0
	s_add_i32 s38, s72, s43
	s_mov_b32 m0, s38
	s_nop 0
	global_load_lds_dwordx4 v130, s[98:99]
	s_add_i32 m0, s38, 0x2000
	s_add_u32 s36, s36, 0x40080
	s_addc_u32 s37, s37, 0
	s_add_i32 s38, s73, s43
	global_load_lds_dwordx4 v134, s[98:99]
	s_mov_b32 m0, s38
	s_nop 0
	global_load_lds_dwordx4 v130, s[36:37]
	s_add_i32 m0, s38, 0x2000
	s_nop 0
	global_load_lds_dwordx4 v134, s[36:37]
	s_mov_b32 m0, s60
	s_nop 0
	global_load_lds_dwordx4 v128, s[100:101]
	s_mov_b32 m0, s61
	s_nop 0
	global_load_lds_dwordx4 v132, s[100:101]
	ds_read_b128 v[186:189], v157 offset:49152
	ds_read_b128 v[190:193], v157 offset:50176
	ds_read_b128 v[194:197], v157 offset:51200
	ds_read_b128 v[198:201], v157 offset:52224
	ds_read_b128 v[202:205], v157 offset:53248
	ds_read_b128 v[206:209], v157 offset:54272
	ds_read_b128 v[210:213], v157 offset:55296
	ds_read_b128 v[214:217], v157 offset:56320
	s_waitcnt vmcnt(8)
	s_waitcnt lgkmcnt(0)
	s_setprio 1
	s_barrier
	v_mfma_f32_16x16x32_bf16 v[60:63], v[146:149], v[186:189], v[60:63]
	v_mfma_f32_16x16x32_bf16 v[56:59], v[162:165], v[186:189], v[56:59]
	v_mfma_f32_16x16x32_bf16 v[44:47], v[146:149], v[194:197], v[44:47]
	v_mfma_f32_16x16x32_bf16 v[40:43], v[162:165], v[194:197], v[40:43]
	v_mfma_f32_16x16x32_bf16 v[28:31], v[146:149], v[202:205], v[28:31]
	v_mfma_f32_16x16x32_bf16 v[24:27], v[162:165], v[202:205], v[24:27]
	v_mfma_f32_16x16x32_bf16 v[12:15], v[146:149], v[210:213], v[12:15]
	v_mfma_f32_16x16x32_bf16 v[8:11], v[162:165], v[210:213], v[8:11]
	v_mfma_f32_16x16x32_bf16 v[60:63], v[158:161], v[190:193], v[60:63]
	v_mfma_f32_16x16x32_bf16 v[56:59], v[166:169], v[190:193], v[56:59]
	v_mfma_f32_16x16x32_bf16 v[44:47], v[158:161], v[198:201], v[44:47]
	v_mfma_f32_16x16x32_bf16 v[40:43], v[166:169], v[198:201], v[40:43]
	v_mfma_f32_16x16x32_bf16 v[28:31], v[158:161], v[206:209], v[28:31]
	v_mfma_f32_16x16x32_bf16 v[24:27], v[166:169], v[206:209], v[24:27]
	v_mfma_f32_16x16x32_bf16 v[12:15], v[158:161], v[214:217], v[12:15]
	v_mfma_f32_16x16x32_bf16 v[8:11], v[166:169], v[214:217], v[8:11]
	s_setprio 0
	s_setprio 1
	v_mfma_f32_16x16x32_bf16 v[52:55], v[170:173], v[186:189], v[52:55]
	v_mfma_f32_16x16x32_bf16 v[48:51], v[178:181], v[186:189], v[48:51]
	v_mfma_f32_16x16x32_bf16 v[36:39], v[170:173], v[194:197], v[36:39]
	v_mfma_f32_16x16x32_bf16 v[32:35], v[178:181], v[194:197], v[32:35]
	v_mfma_f32_16x16x32_bf16 v[20:23], v[170:173], v[202:205], v[20:23]
	v_mfma_f32_16x16x32_bf16 v[16:19], v[178:181], v[202:205], v[16:19]
	v_mfma_f32_16x16x32_bf16 v[4:7], v[170:173], v[210:213], v[4:7]
	v_mfma_f32_16x16x32_bf16 v[0:3], v[178:181], v[210:213], v[0:3]
	v_mfma_f32_16x16x32_bf16 v[52:55], v[174:177], v[190:193], v[52:55]
	v_mfma_f32_16x16x32_bf16 v[48:51], v[182:185], v[190:193], v[48:51]
	v_mfma_f32_16x16x32_bf16 v[36:39], v[174:177], v[198:201], v[36:39]
	v_mfma_f32_16x16x32_bf16 v[32:35], v[182:185], v[198:201], v[32:35]
	v_mfma_f32_16x16x32_bf16 v[20:23], v[174:177], v[206:209], v[20:23]
	v_mfma_f32_16x16x32_bf16 v[16:19], v[182:185], v[206:209], v[16:19]
	v_mfma_f32_16x16x32_bf16 v[4:7], v[174:177], v[214:217], v[4:7]
	v_mfma_f32_16x16x32_bf16 v[0:3], v[182:185], v[214:217], v[0:3]
	s_barrier
	s_setprio 0
	s_add_i32 s71, s71, 2
	s_add_u32 s34, s34, 0x100
	s_addc_u32 s35, s35, 0
	s_add_u32 s69, s69, 0x100
	s_addc_u32 s70, s70, 0
	s_cmp_gt_u32 s71, 13
	s_cbranch_scc0 .LBB0_217
	s_and_b64 vcc, exec, s[14:15]
	s_cbranch_vccz .LBB0_220
	s_barrier

.LBB0_471:
	s_add_u32 s34, s30, 0xfffc0080
	s_addc_u32 s35, s31, -1
	s_cmp_eq_u32 s69, 12
	s_cselect_b32 s37, s21, s35
	s_cselect_b32 s36, s27, s34
	s_cselect_b32 s35, s19, s68
	s_cselect_b32 s34, s64, s65
	s_add_u32 s98, s34, s14
	s_addc_u32 s99, s35, s15
	s_add_u32 s100, s36, s14
	s_addc_u32 s101, s37, s15
	s_add_i32 m0, s29, 0xc000
	s_nop 0
	global_load_lds_dwordx4 v184, s[30:31]
	s_add_i32 m0, s29, 0xe000
	s_nop 0
	global_load_lds_dwordx4 v186, s[30:31]
	ds_read_b128 v[128:131], v207
	ds_read_b128 v[132:135], v207 offset:1024
	ds_read_b128 v[136:139], v207 offset:2048
	ds_read_b128 v[140:143], v207 offset:3072
	ds_read_b128 v[144:147], v208
	ds_read_b128 v[148:151], v208 offset:1024
	ds_read_b128 v[152:155], v208 offset:2048
	ds_read_b128 v[156:159], v208 offset:3072
	ds_read_b128 v[160:163], v209
	ds_read_b128 v[164:167], v209 offset:1024
	ds_read_b128 v[168:171], v209 offset:2048
	ds_read_b128 v[172:175], v209 offset:3072
	ds_read_b128 v[192:195], v209 offset:4096
	ds_read_b128 v[196:199], v209 offset:5120
	ds_read_b128 v[200:203], v209 offset:6144
	ds_read_b128 v[210:213], v209 offset:7168
	s_waitcnt vmcnt(8)
	s_waitcnt lgkmcnt(0)
	s_setprio 1
	s_barrier
	v_mfma_f32_16x16x32_bf16 v[124:127], v[128:131], v[160:163], v[124:127]
	v_mfma_f32_16x16x32_bf16 v[120:123], v[136:139], v[160:163], v[120:123]
	v_mfma_f32_16x16x32_bf16 v[108:111], v[128:131], v[168:171], v[108:111]
	v_mfma_f32_16x16x32_bf16 v[104:107], v[136:139], v[168:171], v[104:107]
	v_mfma_f32_16x16x32_bf16 v[92:95], v[128:131], v[192:195], v[92:95]
	v_mfma_f32_16x16x32_bf16 v[88:91], v[136:139], v[192:195], v[88:91]
	v_mfma_f32_16x16x32_bf16 v[76:79], v[128:131], v[200:203], v[76:79]
	v_mfma_f32_16x16x32_bf16 v[72:75], v[136:139], v[200:203], v[72:75]
	v_mfma_f32_16x16x32_bf16 v[124:127], v[132:135], v[164:167], v[124:127]
	v_mfma_f32_16x16x32_bf16 v[120:123], v[140:143], v[164:167], v[120:123]
	v_mfma_f32_16x16x32_bf16 v[108:111], v[132:135], v[172:175], v[108:111]
	v_mfma_f32_16x16x32_bf16 v[104:107], v[140:143], v[172:175], v[104:107]
	v_mfma_f32_16x16x32_bf16 v[92:95], v[132:135], v[196:199], v[92:95]
	v_mfma_f32_16x16x32_bf16 v[88:91], v[140:143], v[196:199], v[88:91]
	v_mfma_f32_16x16x32_bf16 v[76:79], v[132:135], v[210:213], v[76:79]
	v_mfma_f32_16x16x32_bf16 v[72:75], v[140:143], v[210:213], v[72:75]
	s_setprio 0
	s_setprio 1
	v_mfma_f32_16x16x32_bf16 v[116:119], v[144:147], v[160:163], v[116:119]
	v_mfma_f32_16x16x32_bf16 v[112:115], v[152:155], v[160:163], v[112:115]
	v_mfma_f32_16x16x32_bf16 v[100:103], v[144:147], v[168:171], v[100:103]
	v_mfma_f32_16x16x32_bf16 v[96:99], v[152:155], v[168:171], v[96:99]
	v_mfma_f32_16x16x32_bf16 v[84:87], v[144:147], v[192:195], v[84:87]
	v_mfma_f32_16x16x32_bf16 v[80:83], v[152:155], v[192:195], v[80:83]
	v_mfma_f32_16x16x32_bf16 v[68:71], v[144:147], v[200:203], v[68:71]
	v_mfma_f32_16x16x32_bf16 v[64:67], v[152:155], v[200:203], v[64:67]
	v_mfma_f32_16x16x32_bf16 v[116:119], v[148:151], v[164:167], v[116:119]
	v_mfma_f32_16x16x32_bf16 v[112:115], v[156:159], v[164:167], v[112:115]
	v_mfma_f32_16x16x32_bf16 v[100:103], v[148:151], v[172:175], v[100:103]
	v_mfma_f32_16x16x32_bf16 v[96:99], v[156:159], v[172:175], v[96:99]
	v_mfma_f32_16x16x32_bf16 v[84:87], v[148:151], v[196:199], v[84:87]
	v_mfma_f32_16x16x32_bf16 v[80:83], v[156:159], v[196:199], v[80:83]
	v_mfma_f32_16x16x32_bf16 v[68:71], v[148:151], v[210:213], v[68:71]
	v_mfma_f32_16x16x32_bf16 v[64:67], v[156:159], v[210:213], v[64:67]
	s_barrier
	s_setprio 0
	s_add_i32 s70, s62, s40
	s_mov_b32 m0, s70
	s_nop 0
	global_load_lds_dwordx4 v178, s[34:35]
	s_add_i32 m0, s70, 0x2000
	s_add_u32 s70, s34, 0x40000
	s_addc_u32 s71, s35, 0
	s_add_i32 s72, s63, s40
	global_load_lds_dwordx4 v182, s[34:35]
	s_mov_b32 m0, s72
	s_nop 0
	global_load_lds_dwordx4 v178, s[70:71]
	s_add_i32 m0, s72, 0x2000
	s_nop 0
	global_load_lds_dwordx4 v182, s[70:71]
	s_mov_b32 m0, s29
	s_nop 0
	global_load_lds_dwordx4 v176, s[36:37]
	s_mov_b32 m0, s41
	s_nop 0
	global_load_lds_dwordx4 v180, s[36:37]
	ds_read_b128 v[160:163], v209 offset:16384
	ds_read_b128 v[164:167], v209 offset:17408
	ds_read_b128 v[168:171], v209 offset:18432
	ds_read_b128 v[172:175], v209 offset:19456
	ds_read_b128 v[192:195], v209 offset:20480
	ds_read_b128 v[196:199], v209 offset:21504
	ds_read_b128 v[200:203], v209 offset:22528
	ds_read_b128 v[210:213], v209 offset:23552
	s_waitcnt vmcnt(8)
	s_waitcnt lgkmcnt(0)
	s_setprio 1
	s_barrier
	v_mfma_f32_16x16x32_bf16 v[60:63], v[128:131], v[160:163], v[60:63]
	v_mfma_f32_16x16x32_bf16 v[56:59], v[136:139], v[160:163], v[56:59]
	v_mfma_f32_16x16x32_bf16 v[44:47], v[128:131], v[168:171], v[44:47]
	v_mfma_f32_16x16x32_bf16 v[40:43], v[136:139], v[168:171], v[40:43]
	v_mfma_f32_16x16x32_bf16 v[28:31], v[128:131], v[192:195], v[28:31]
	v_mfma_f32_16x16x32_bf16 v[24:27], v[136:139], v[192:195], v[24:27]
	v_mfma_f32_16x16x32_bf16 v[12:15], v[128:131], v[200:203], v[12:15]
	v_mfma_f32_16x16x32_bf16 v[8:11], v[136:139], v[200:203], v[8:11]
	v_mfma_f32_16x16x32_bf16 v[60:63], v[132:135], v[164:167], v[60:63]
	v_mfma_f32_16x16x32_bf16 v[56:59], v[140:143], v[164:167], v[56:59]
	v_mfma_f32_16x16x32_bf16 v[44:47], v[132:135], v[172:175], v[44:47]
	v_mfma_f32_16x16x32_bf16 v[40:43], v[140:143], v[172:175], v[40:43]
	v_mfma_f32_16x16x32_bf16 v[28:31], v[132:135], v[196:199], v[28:31]
	v_mfma_f32_16x16x32_bf16 v[24:27], v[140:143], v[196:199], v[24:27]
	v_mfma_f32_16x16x32_bf16 v[12:15], v[132:135], v[210:213], v[12:15]
	v_mfma_f32_16x16x32_bf16 v[8:11], v[140:143], v[210:213], v[8:11]
	s_setprio 0
	s_setprio 1
	v_mfma_f32_16x16x32_bf16 v[52:55], v[144:147], v[160:163], v[52:55]
	v_mfma_f32_16x16x32_bf16 v[48:51], v[152:155], v[160:163], v[48:51]
	v_mfma_f32_16x16x32_bf16 v[36:39], v[144:147], v[168:171], v[36:39]
	v_mfma_f32_16x16x32_bf16 v[32:35], v[152:155], v[168:171], v[32:35]
	v_mfma_f32_16x16x32_bf16 v[20:23], v[144:147], v[192:195], v[20:23]
	v_mfma_f32_16x16x32_bf16 v[16:19], v[152:155], v[192:195], v[16:19]
	v_mfma_f32_16x16x32_bf16 v[4:7], v[144:147], v[200:203], v[4:7]
	v_mfma_f32_16x16x32_bf16 v[0:3], v[152:155], v[200:203], v[0:3]
	v_mfma_f32_16x16x32_bf16 v[52:55], v[148:151], v[164:167], v[52:55]
	v_mfma_f32_16x16x32_bf16 v[48:51], v[156:159], v[164:167], v[48:51]
	v_mfma_f32_16x16x32_bf16 v[36:39], v[148:151], v[172:175], v[36:39]
	v_mfma_f32_16x16x32_bf16 v[32:35], v[156:159], v[172:175], v[32:35]
	v_mfma_f32_16x16x32_bf16 v[20:23], v[148:151], v[196:199], v[20:23]
	v_mfma_f32_16x16x32_bf16 v[16:19], v[156:159], v[196:199], v[16:19]
	v_mfma_f32_16x16x32_bf16 v[4:7], v[148:151], v[210:213], v[4:7]
	v_mfma_f32_16x16x32_bf16 v[0:3], v[156:159], v[210:213], v[0:3]
	s_barrier
	s_setprio 0
	s_add_i32 s70, 0, 0x18000
	s_add_i32 s71, 0, 0x1c000
	s_add_u32 s36, s36, 0x40000
	s_addc_u32 s37, s37, 0
	s_mov_b32 m0, s42
	s_nop 0
	global_load_lds_dwordx4 v176, s[36:37]
	s_mov_b32 m0, s43
	s_nop 0
	global_load_lds_dwordx4 v180, s[36:37]
	v_add_u32_e32 v140, s70, v206
	v_add_u32_e32 v156, s71, v206
	ds_read_b128 v[128:131], v140
	ds_read_b128 v[132:135], v140 offset:1024
	ds_read_b128 v[136:139], v140 offset:2048
	ds_read_b128 v[140:143], v140 offset:3072
	ds_read_b128 v[144:147], v156
	ds_read_b128 v[148:151], v156 offset:1024
	ds_read_b128 v[152:155], v156 offset:2048
	ds_read_b128 v[156:159], v156 offset:3072
	ds_read_b128 v[160:163], v209 offset:32768
	ds_read_b128 v[164:167], v209 offset:33792
	ds_read_b128 v[168:171], v209 offset:34816
	ds_read_b128 v[172:175], v209 offset:35840
	ds_read_b128 v[192:195], v209 offset:36864
	ds_read_b128 v[196:199], v209 offset:37888
	ds_read_b128 v[200:203], v209 offset:38912
	ds_read_b128 v[210:213], v209 offset:39936
	s_waitcnt vmcnt(8)
	s_waitcnt lgkmcnt(0)
	s_setprio 1
	s_barrier
	v_mfma_f32_16x16x32_bf16 v[124:127], v[128:131], v[160:163], v[124:127]
	v_mfma_f32_16x16x32_bf16 v[120:123], v[136:139], v[160:163], v[120:123]
	v_mfma_f32_16x16x32_bf16 v[108:111], v[128:131], v[168:171], v[108:111]
	v_mfma_f32_16x16x32_bf16 v[104:107], v[136:139], v[168:171], v[104:107]
	v_mfma_f32_16x16x32_bf16 v[92:95], v[128:131], v[192:195], v[92:95]
	v_mfma_f32_16x16x32_bf16 v[88:91], v[136:139], v[192:195], v[88:91]
	v_mfma_f32_16x16x32_bf16 v[76:79], v[128:131], v[200:203], v[76:79]
	v_mfma_f32_16x16x32_bf16 v[72:75], v[136:139], v[200:203], v[72:75]
	v_mfma_f32_16x16x32_bf16 v[124:127], v[132:135], v[164:167], v[124:127]
	v_mfma_f32_16x16x32_bf16 v[120:123], v[140:143], v[164:167], v[120:123]
	v_mfma_f32_16x16x32_bf16 v[108:111], v[132:135], v[172:175], v[108:111]
	v_mfma_f32_16x16x32_bf16 v[104:107], v[140:143], v[172:175], v[104:107]
	v_mfma_f32_16x16x32_bf16 v[92:95], v[132:135], v[196:199], v[92:95]
	v_mfma_f32_16x16x32_bf16 v[88:91], v[140:143], v[196:199], v[88:91]
	v_mfma_f32_16x16x32_bf16 v[76:79], v[132:135], v[210:213], v[76:79]
	v_mfma_f32_16x16x32_bf16 v[72:75], v[140:143], v[210:213], v[72:75]
	s_setprio 0
	s_setprio 1
	v_mfma_f32_16x16x32_bf16 v[116:119], v[144:147], v[160:163], v[116:119]
	v_mfma_f32_16x16x32_bf16 v[112:115], v[152:155], v[160:163], v[112:115]
	v_mfma_f32_16x16x32_bf16 v[100:103], v[144:147], v[168:171], v[100:103]
	v_mfma_f32_16x16x32_bf16 v[96:99], v[152:155], v[168:171], v[96:99]
	v_mfma_f32_16x16x32_bf16 v[84:87], v[144:147], v[192:195], v[84:87]
	v_mfma_f32_16x16x32_bf16 v[80:83], v[152:155], v[192:195], v[80:83]
	v_mfma_f32_16x16x32_bf16 v[68:71], v[144:147], v[200:203], v[68:71]
	v_mfma_f32_16x16x32_bf16 v[64:67], v[152:155], v[200:203], v[64:67]
	v_mfma_f32_16x16x32_bf16 v[116:119], v[148:151], v[164:167], v[116:119]
	v_mfma_f32_16x16x32_bf16 v[112:115], v[156:159], v[164:167], v[112:115]
	v_mfma_f32_16x16x32_bf16 v[100:103], v[148:151], v[172:175], v[100:103]
	v_mfma_f32_16x16x32_bf16 v[96:99], v[156:159], v[172:175], v[96:99]
	v_mfma_f32_16x16x32_bf16 v[84:87], v[148:151], v[196:199], v[84:87]
	v_mfma_f32_16x16x32_bf16 v[80:83], v[156:159], v[196:199], v[80:83]
	v_mfma_f32_16x16x32_bf16 v[68:71], v[148:151], v[210:213], v[68:71]
	v_mfma_f32_16x16x32_bf16 v[64:67], v[156:159], v[210:213], v[64:67]
	s_barrier
	s_setprio 0
	s_add_i32 s36, s70, s40
	s_mov_b32 m0, s36
	s_nop 0
	global_load_lds_dwordx4 v178, s[98:99]
	s_add_i32 m0, s36, 0x2000
	s_add_u32 s34, s34, 0x40080
	s_addc_u32 s35, s35, 0
	s_add_i32 s36, s71, s40
	global_load_lds_dwordx4 v182, s[98:99]
	s_mov_b32 m0, s36
	s_nop 0
	global_load_lds_dwordx4 v178, s[34:35]
	s_add_i32 m0, s36, 0x2000
	s_nop 0
	global_load_lds_dwordx4 v182, s[34:35]
	s_mov_b32 m0, s49
	s_nop 0
	global_load_lds_dwordx4 v176, s[100:101]
	s_mov_b32 m0, s50
	s_nop 0
	global_load_lds_dwordx4 v180, s[100:101]
	ds_read_b128 v[160:163], v209 offset:49152
	ds_read_b128 v[164:167], v209 offset:50176
	ds_read_b128 v[168:171], v209 offset:51200
	ds_read_b128 v[172:175], v209 offset:52224
	ds_read_b128 v[192:195], v209 offset:53248
	ds_read_b128 v[196:199], v209 offset:54272
	ds_read_b128 v[200:203], v209 offset:55296
	ds_read_b128 v[210:213], v209 offset:56320
	s_waitcnt vmcnt(8)
	s_waitcnt lgkmcnt(0)
	s_setprio 1
	s_barrier
	v_mfma_f32_16x16x32_bf16 v[60:63], v[128:131], v[160:163], v[60:63]
	v_mfma_f32_16x16x32_bf16 v[56:59], v[136:139], v[160:163], v[56:59]
	v_mfma_f32_16x16x32_bf16 v[44:47], v[128:131], v[168:171], v[44:47]
	v_mfma_f32_16x16x32_bf16 v[40:43], v[136:139], v[168:171], v[40:43]
	v_mfma_f32_16x16x32_bf16 v[28:31], v[128:131], v[192:195], v[28:31]
	v_mfma_f32_16x16x32_bf16 v[24:27], v[136:139], v[192:195], v[24:27]
	v_mfma_f32_16x16x32_bf16 v[12:15], v[128:131], v[200:203], v[12:15]
	v_mfma_f32_16x16x32_bf16 v[8:11], v[136:139], v[200:203], v[8:11]
	v_mfma_f32_16x16x32_bf16 v[60:63], v[132:135], v[164:167], v[60:63]
	v_mfma_f32_16x16x32_bf16 v[56:59], v[140:143], v[164:167], v[56:59]
	v_mfma_f32_16x16x32_bf16 v[44:47], v[132:135], v[172:175], v[44:47]
	v_mfma_f32_16x16x32_bf16 v[40:43], v[140:143], v[172:175], v[40:43]
	v_mfma_f32_16x16x32_bf16 v[28:31], v[132:135], v[196:199], v[28:31]
	v_mfma_f32_16x16x32_bf16 v[24:27], v[140:143], v[196:199], v[24:27]
	v_mfma_f32_16x16x32_bf16 v[12:15], v[132:135], v[210:213], v[12:15]
	v_mfma_f32_16x16x32_bf16 v[8:11], v[140:143], v[210:213], v[8:11]
	s_setprio 0
	s_setprio 1
	v_mfma_f32_16x16x32_bf16 v[52:55], v[144:147], v[160:163], v[52:55]
	v_mfma_f32_16x16x32_bf16 v[48:51], v[152:155], v[160:163], v[48:51]
	v_mfma_f32_16x16x32_bf16 v[36:39], v[144:147], v[168:171], v[36:39]
	v_mfma_f32_16x16x32_bf16 v[32:35], v[152:155], v[168:171], v[32:35]
	v_mfma_f32_16x16x32_bf16 v[20:23], v[144:147], v[192:195], v[20:23]
	v_mfma_f32_16x16x32_bf16 v[16:19], v[152:155], v[192:195], v[16:19]
	v_mfma_f32_16x16x32_bf16 v[4:7], v[144:147], v[200:203], v[4:7]
	v_mfma_f32_16x16x32_bf16 v[0:3], v[152:155], v[200:203], v[0:3]
	v_mfma_f32_16x16x32_bf16 v[52:55], v[148:151], v[164:167], v[52:55]
	v_mfma_f32_16x16x32_bf16 v[48:51], v[156:159], v[164:167], v[48:51]
	v_mfma_f32_16x16x32_bf16 v[36:39], v[148:151], v[172:175], v[36:39]
	v_mfma_f32_16x16x32_bf16 v[32:35], v[156:159], v[172:175], v[32:35]
	v_mfma_f32_16x16x32_bf16 v[20:23], v[148:151], v[196:199], v[20:23]
	v_mfma_f32_16x16x32_bf16 v[16:19], v[156:159], v[196:199], v[16:19]
	v_mfma_f32_16x16x32_bf16 v[4:7], v[148:151], v[210:213], v[4:7]
	v_mfma_f32_16x16x32_bf16 v[0:3], v[156:159], v[210:213], v[0:3]
	s_barrier
	s_setprio 0
	s_add_i32 s69, s69, 2
	s_add_u32 s30, s30, 0x100
	s_addc_u32 s31, s31, 0
	s_add_u32 s65, s65, 0x100
	s_addc_u32 s68, s68, 0
	s_cmp_gt_u32 s69, 13
	s_cbranch_scc0 .LBB0_471
	s_and_b64 vcc, exec, s[16:17]
	s_cbranch_vccz .LBB0_474
	s_barrier

.LBB0_555:
	s_add_u32 s30, s28, 0xfffc0080
	s_addc_u32 s31, s29, -1
	s_cmp_eq_u32 s63, 12
	s_cselect_b32 s35, s19, s31
	s_cselect_b32 s34, s51, s30
	s_cselect_b32 s31, s17, s62
	s_cselect_b32 s30, s60, s61
	s_add_u32 s98, s30, s12
	s_addc_u32 s99, s31, s13
	s_add_u32 s100, s34, s12
	s_addc_u32 s101, s35, s13
	s_add_i32 m0, s25, 0xc000
	s_nop 0
	global_load_lds_dwordx4 v136, s[28:29]
	s_add_i32 m0, s25, 0xe000
	s_nop 0
	global_load_lds_dwordx4 v138, s[28:29]
	ds_read_b128 v[154:157], v149
	ds_read_b128 v[158:161], v149 offset:1024
	ds_read_b128 v[162:165], v149 offset:2048
	ds_read_b128 v[166:169], v149 offset:3072
	ds_read_b128 v[170:173], v150
	ds_read_b128 v[174:177], v150 offset:1024
	ds_read_b128 v[178:181], v150 offset:2048
	ds_read_b128 v[182:185], v150 offset:3072
	ds_read_b128 v[186:189], v151
	ds_read_b128 v[190:193], v151 offset:1024
	ds_read_b128 v[194:197], v151 offset:2048
	ds_read_b128 v[198:201], v151 offset:3072
	ds_read_b128 v[202:205], v151 offset:4096
	ds_read_b128 v[206:209], v151 offset:5120
	ds_read_b128 v[210:213], v151 offset:6144
	ds_read_b128 v[214:217], v151 offset:7168
	s_waitcnt vmcnt(8)
	s_waitcnt lgkmcnt(0)
	s_setprio 1
	s_barrier
	v_mfma_f32_16x16x32_bf16 v[116:119], v[154:157], v[186:189], v[116:119]
	v_mfma_f32_16x16x32_bf16 v[112:115], v[162:165], v[186:189], v[112:115]
	v_mfma_f32_16x16x32_bf16 v[108:111], v[154:157], v[194:197], v[108:111]
	v_mfma_f32_16x16x32_bf16 v[100:103], v[162:165], v[194:197], v[100:103]
	v_mfma_f32_16x16x32_bf16 v[92:95], v[154:157], v[202:205], v[92:95]
	v_mfma_f32_16x16x32_bf16 v[84:87], v[162:165], v[202:205], v[84:87]
	v_mfma_f32_16x16x32_bf16 v[76:79], v[154:157], v[210:213], v[76:79]
	v_mfma_f32_16x16x32_bf16 v[68:71], v[162:165], v[210:213], v[68:71]
	v_mfma_f32_16x16x32_bf16 v[116:119], v[158:161], v[190:193], v[116:119]
	v_mfma_f32_16x16x32_bf16 v[112:115], v[166:169], v[190:193], v[112:115]
	v_mfma_f32_16x16x32_bf16 v[108:111], v[158:161], v[198:201], v[108:111]
	v_mfma_f32_16x16x32_bf16 v[100:103], v[166:169], v[198:201], v[100:103]
	v_mfma_f32_16x16x32_bf16 v[92:95], v[158:161], v[206:209], v[92:95]
	v_mfma_f32_16x16x32_bf16 v[84:87], v[166:169], v[206:209], v[84:87]
	v_mfma_f32_16x16x32_bf16 v[76:79], v[158:161], v[214:217], v[76:79]
	v_mfma_f32_16x16x32_bf16 v[68:71], v[166:169], v[214:217], v[68:71]
	s_setprio 0
	s_setprio 1
	v_mfma_f32_16x16x32_bf16 v[124:127], v[170:173], v[186:189], v[124:127]
	v_mfma_f32_16x16x32_bf16 v[120:123], v[178:181], v[186:189], v[120:123]
	v_mfma_f32_16x16x32_bf16 v[104:107], v[170:173], v[194:197], v[104:107]
	v_mfma_f32_16x16x32_bf16 v[96:99], v[178:181], v[194:197], v[96:99]
	v_mfma_f32_16x16x32_bf16 v[88:91], v[170:173], v[202:205], v[88:91]
	v_mfma_f32_16x16x32_bf16 v[80:83], v[178:181], v[202:205], v[80:83]
	v_mfma_f32_16x16x32_bf16 v[72:75], v[170:173], v[210:213], v[72:75]
	v_mfma_f32_16x16x32_bf16 v[64:67], v[178:181], v[210:213], v[64:67]
	v_mfma_f32_16x16x32_bf16 v[124:127], v[174:177], v[190:193], v[124:127]
	v_mfma_f32_16x16x32_bf16 v[120:123], v[182:185], v[190:193], v[120:123]
	v_mfma_f32_16x16x32_bf16 v[104:107], v[174:177], v[198:201], v[104:107]
	v_mfma_f32_16x16x32_bf16 v[96:99], v[182:185], v[198:201], v[96:99]
	v_mfma_f32_16x16x32_bf16 v[88:91], v[174:177], v[206:209], v[88:91]
	v_mfma_f32_16x16x32_bf16 v[80:83], v[182:185], v[206:209], v[80:83]
	v_mfma_f32_16x16x32_bf16 v[72:75], v[174:177], v[214:217], v[72:75]
	v_mfma_f32_16x16x32_bf16 v[64:67], v[182:185], v[214:217], v[64:67]
	s_barrier
	s_setprio 0
	s_add_i32 s64, s48, s36
	s_mov_b32 m0, s64
	s_nop 0
	global_load_lds_dwordx4 v132, s[30:31]
	s_add_i32 m0, s64, 0x2000
	s_add_u32 s64, s30, 0x40000
	s_addc_u32 s65, s31, 0
	s_add_i32 s68, s49, s36
	global_load_lds_dwordx4 v128, s[30:31]
	s_mov_b32 m0, s68
	s_nop 0
	global_load_lds_dwordx4 v132, s[64:65]
	s_add_i32 m0, s68, 0x2000
	s_nop 0
	global_load_lds_dwordx4 v128, s[64:65]
	s_mov_b32 m0, s25
	s_nop 0
	global_load_lds_dwordx4 v134, s[34:35]
	s_mov_b32 m0, s27
	s_nop 0
	global_load_lds_dwordx4 v130, s[34:35]
	ds_read_b128 v[186:189], v151 offset:16384
	ds_read_b128 v[190:193], v151 offset:17408
	ds_read_b128 v[194:197], v151 offset:18432
	ds_read_b128 v[198:201], v151 offset:19456
	ds_read_b128 v[202:205], v151 offset:20480
	ds_read_b128 v[206:209], v151 offset:21504
	ds_read_b128 v[210:213], v151 offset:22528
	ds_read_b128 v[214:217], v151 offset:23552
	s_waitcnt vmcnt(8)
	s_waitcnt lgkmcnt(0)
	s_setprio 1
	s_barrier
	v_mfma_f32_16x16x32_bf16 v[60:63], v[154:157], v[186:189], v[60:63]
	v_mfma_f32_16x16x32_bf16 v[52:55], v[162:165], v[186:189], v[52:55]
	v_mfma_f32_16x16x32_bf16 v[44:47], v[154:157], v[194:197], v[44:47]
	v_mfma_f32_16x16x32_bf16 v[36:39], v[162:165], v[194:197], v[36:39]
	v_mfma_f32_16x16x32_bf16 v[28:31], v[154:157], v[202:205], v[28:31]
	v_mfma_f32_16x16x32_bf16 v[20:23], v[162:165], v[202:205], v[20:23]
	v_mfma_f32_16x16x32_bf16 v[12:15], v[154:157], v[210:213], v[12:15]
	v_mfma_f32_16x16x32_bf16 v[4:7], v[162:165], v[210:213], v[4:7]
	v_mfma_f32_16x16x32_bf16 v[60:63], v[158:161], v[190:193], v[60:63]
	v_mfma_f32_16x16x32_bf16 v[52:55], v[166:169], v[190:193], v[52:55]
	v_mfma_f32_16x16x32_bf16 v[44:47], v[158:161], v[198:201], v[44:47]
	v_mfma_f32_16x16x32_bf16 v[36:39], v[166:169], v[198:201], v[36:39]
	v_mfma_f32_16x16x32_bf16 v[28:31], v[158:161], v[206:209], v[28:31]
	v_mfma_f32_16x16x32_bf16 v[20:23], v[166:169], v[206:209], v[20:23]
	v_mfma_f32_16x16x32_bf16 v[12:15], v[158:161], v[214:217], v[12:15]
	v_mfma_f32_16x16x32_bf16 v[4:7], v[166:169], v[214:217], v[4:7]
	s_setprio 0
	s_setprio 1
	v_mfma_f32_16x16x32_bf16 v[56:59], v[170:173], v[186:189], v[56:59]
	v_mfma_f32_16x16x32_bf16 v[48:51], v[178:181], v[186:189], v[48:51]
	v_mfma_f32_16x16x32_bf16 v[40:43], v[170:173], v[194:197], v[40:43]
	v_mfma_f32_16x16x32_bf16 v[32:35], v[178:181], v[194:197], v[32:35]
	v_mfma_f32_16x16x32_bf16 v[24:27], v[170:173], v[202:205], v[24:27]
	v_mfma_f32_16x16x32_bf16 v[16:19], v[178:181], v[202:205], v[16:19]
	v_mfma_f32_16x16x32_bf16 v[8:11], v[170:173], v[210:213], v[8:11]
	v_mfma_f32_16x16x32_bf16 v[0:3], v[178:181], v[210:213], v[0:3]
	v_mfma_f32_16x16x32_bf16 v[56:59], v[174:177], v[190:193], v[56:59]
	v_mfma_f32_16x16x32_bf16 v[48:51], v[182:185], v[190:193], v[48:51]
	v_mfma_f32_16x16x32_bf16 v[40:43], v[174:177], v[198:201], v[40:43]
	v_mfma_f32_16x16x32_bf16 v[32:35], v[182:185], v[198:201], v[32:35]
	v_mfma_f32_16x16x32_bf16 v[24:27], v[174:177], v[206:209], v[24:27]
	v_mfma_f32_16x16x32_bf16 v[16:19], v[182:185], v[206:209], v[16:19]
	v_mfma_f32_16x16x32_bf16 v[8:11], v[174:177], v[214:217], v[8:11]
	v_mfma_f32_16x16x32_bf16 v[0:3], v[182:185], v[214:217], v[0:3]
	s_barrier
	s_setprio 0
	s_add_i32 s64, 0, 0x18000
	s_add_i32 s65, 0, 0x1c000
	s_add_u32 s34, s34, 0x40000
	s_addc_u32 s35, s35, 0
	s_mov_b32 m0, s39
	s_nop 0
	global_load_lds_dwordx4 v134, s[34:35]
	s_mov_b32 m0, s40
	s_nop 0
	global_load_lds_dwordx4 v130, s[34:35]
	v_add_u32_e32 v153, s64, v147
	ds_read_b128 v[154:157], v153
	ds_read_b128 v[158:161], v153 offset:1024
	ds_read_b128 v[162:165], v153 offset:2048
	ds_read_b128 v[166:169], v153 offset:3072
	v_add_u32_e32 v153, s65, v147
	ds_read_b128 v[170:173], v153
	ds_read_b128 v[174:177], v153 offset:1024
	ds_read_b128 v[178:181], v153 offset:2048
	ds_read_b128 v[182:185], v153 offset:3072
	ds_read_b128 v[186:189], v151 offset:32768
	ds_read_b128 v[190:193], v151 offset:33792
	ds_read_b128 v[194:197], v151 offset:34816
	ds_read_b128 v[198:201], v151 offset:35840
	ds_read_b128 v[202:205], v151 offset:36864
	ds_read_b128 v[206:209], v151 offset:37888
	ds_read_b128 v[210:213], v151 offset:38912
	ds_read_b128 v[214:217], v151 offset:39936
	s_waitcnt vmcnt(8)
	s_waitcnt lgkmcnt(0)
	s_setprio 1
	s_barrier
	v_mfma_f32_16x16x32_bf16 v[116:119], v[154:157], v[186:189], v[116:119]
	v_mfma_f32_16x16x32_bf16 v[112:115], v[162:165], v[186:189], v[112:115]
	v_mfma_f32_16x16x32_bf16 v[108:111], v[154:157], v[194:197], v[108:111]
	v_mfma_f32_16x16x32_bf16 v[100:103], v[162:165], v[194:197], v[100:103]
	v_mfma_f32_16x16x32_bf16 v[92:95], v[154:157], v[202:205], v[92:95]
	v_mfma_f32_16x16x32_bf16 v[84:87], v[162:165], v[202:205], v[84:87]
	v_mfma_f32_16x16x32_bf16 v[76:79], v[154:157], v[210:213], v[76:79]
	v_mfma_f32_16x16x32_bf16 v[68:71], v[162:165], v[210:213], v[68:71]
	v_mfma_f32_16x16x32_bf16 v[116:119], v[158:161], v[190:193], v[116:119]
	v_mfma_f32_16x16x32_bf16 v[112:115], v[166:169], v[190:193], v[112:115]
	v_mfma_f32_16x16x32_bf16 v[108:111], v[158:161], v[198:201], v[108:111]
	v_mfma_f32_16x16x32_bf16 v[100:103], v[166:169], v[198:201], v[100:103]
	v_mfma_f32_16x16x32_bf16 v[92:95], v[158:161], v[206:209], v[92:95]
	v_mfma_f32_16x16x32_bf16 v[84:87], v[166:169], v[206:209], v[84:87]
	v_mfma_f32_16x16x32_bf16 v[76:79], v[158:161], v[214:217], v[76:79]
	v_mfma_f32_16x16x32_bf16 v[68:71], v[166:169], v[214:217], v[68:71]
	s_setprio 0
	s_setprio 1
	v_mfma_f32_16x16x32_bf16 v[124:127], v[170:173], v[186:189], v[124:127]
	v_mfma_f32_16x16x32_bf16 v[120:123], v[178:181], v[186:189], v[120:123]
	v_mfma_f32_16x16x32_bf16 v[104:107], v[170:173], v[194:197], v[104:107]
	v_mfma_f32_16x16x32_bf16 v[96:99], v[178:181], v[194:197], v[96:99]
	v_mfma_f32_16x16x32_bf16 v[88:91], v[170:173], v[202:205], v[88:91]
	v_mfma_f32_16x16x32_bf16 v[80:83], v[178:181], v[202:205], v[80:83]
	v_mfma_f32_16x16x32_bf16 v[72:75], v[170:173], v[210:213], v[72:75]
	v_mfma_f32_16x16x32_bf16 v[64:67], v[178:181], v[210:213], v[64:67]
	v_mfma_f32_16x16x32_bf16 v[124:127], v[174:177], v[190:193], v[124:127]
	v_mfma_f32_16x16x32_bf16 v[120:123], v[182:185], v[190:193], v[120:123]
	v_mfma_f32_16x16x32_bf16 v[104:107], v[174:177], v[198:201], v[104:107]
	v_mfma_f32_16x16x32_bf16 v[96:99], v[182:185], v[198:201], v[96:99]
	v_mfma_f32_16x16x32_bf16 v[88:91], v[174:177], v[206:209], v[88:91]
	v_mfma_f32_16x16x32_bf16 v[80:83], v[182:185], v[206:209], v[80:83]
	v_mfma_f32_16x16x32_bf16 v[72:75], v[174:177], v[214:217], v[72:75]
	v_mfma_f32_16x16x32_bf16 v[64:67], v[182:185], v[214:217], v[64:67]
	s_barrier
	s_setprio 0
	s_add_i32 s34, s64, s36
	s_mov_b32 m0, s34
	s_nop 0
	global_load_lds_dwordx4 v132, s[98:99]
	s_add_i32 m0, s34, 0x2000
	s_add_u32 s30, s30, 0x40080
	s_addc_u32 s31, s31, 0
	s_add_i32 s34, s65, s36
	global_load_lds_dwordx4 v128, s[98:99]
	s_mov_b32 m0, s34
	s_nop 0
	global_load_lds_dwordx4 v132, s[30:31]
	s_add_i32 m0, s34, 0x2000
	s_nop 0
	global_load_lds_dwordx4 v128, s[30:31]
	s_mov_b32 m0, s42
	s_nop 0
	global_load_lds_dwordx4 v134, s[100:101]
	s_mov_b32 m0, s43
	s_nop 0
	global_load_lds_dwordx4 v130, s[100:101]
	ds_read_b128 v[186:189], v151 offset:49152
	ds_read_b128 v[190:193], v151 offset:50176
	ds_read_b128 v[194:197], v151 offset:51200
	ds_read_b128 v[198:201], v151 offset:52224
	ds_read_b128 v[202:205], v151 offset:53248
	ds_read_b128 v[206:209], v151 offset:54272
	ds_read_b128 v[210:213], v151 offset:55296
	ds_read_b128 v[214:217], v151 offset:56320
	s_waitcnt vmcnt(8)
	s_waitcnt lgkmcnt(0)
	s_setprio 1
	s_barrier
	v_mfma_f32_16x16x32_bf16 v[60:63], v[154:157], v[186:189], v[60:63]
	v_mfma_f32_16x16x32_bf16 v[52:55], v[162:165], v[186:189], v[52:55]
	v_mfma_f32_16x16x32_bf16 v[44:47], v[154:157], v[194:197], v[44:47]
	v_mfma_f32_16x16x32_bf16 v[36:39], v[162:165], v[194:197], v[36:39]
	v_mfma_f32_16x16x32_bf16 v[28:31], v[154:157], v[202:205], v[28:31]
	v_mfma_f32_16x16x32_bf16 v[20:23], v[162:165], v[202:205], v[20:23]
	v_mfma_f32_16x16x32_bf16 v[12:15], v[154:157], v[210:213], v[12:15]
	v_mfma_f32_16x16x32_bf16 v[4:7], v[162:165], v[210:213], v[4:7]
	v_mfma_f32_16x16x32_bf16 v[60:63], v[158:161], v[190:193], v[60:63]
	v_mfma_f32_16x16x32_bf16 v[52:55], v[166:169], v[190:193], v[52:55]
	v_mfma_f32_16x16x32_bf16 v[44:47], v[158:161], v[198:201], v[44:47]
	v_mfma_f32_16x16x32_bf16 v[36:39], v[166:169], v[198:201], v[36:39]
	v_mfma_f32_16x16x32_bf16 v[28:31], v[158:161], v[206:209], v[28:31]
	v_mfma_f32_16x16x32_bf16 v[20:23], v[166:169], v[206:209], v[20:23]
	v_mfma_f32_16x16x32_bf16 v[12:15], v[158:161], v[214:217], v[12:15]
	v_mfma_f32_16x16x32_bf16 v[4:7], v[166:169], v[214:217], v[4:7]
	s_setprio 0
	s_setprio 1
	v_mfma_f32_16x16x32_bf16 v[56:59], v[170:173], v[186:189], v[56:59]
	v_mfma_f32_16x16x32_bf16 v[48:51], v[178:181], v[186:189], v[48:51]
	v_mfma_f32_16x16x32_bf16 v[40:43], v[170:173], v[194:197], v[40:43]
	v_mfma_f32_16x16x32_bf16 v[32:35], v[178:181], v[194:197], v[32:35]
	v_mfma_f32_16x16x32_bf16 v[24:27], v[170:173], v[202:205], v[24:27]
	v_mfma_f32_16x16x32_bf16 v[16:19], v[178:181], v[202:205], v[16:19]
	v_mfma_f32_16x16x32_bf16 v[8:11], v[170:173], v[210:213], v[8:11]
	v_mfma_f32_16x16x32_bf16 v[0:3], v[178:181], v[210:213], v[0:3]
	v_mfma_f32_16x16x32_bf16 v[56:59], v[174:177], v[190:193], v[56:59]
	v_mfma_f32_16x16x32_bf16 v[48:51], v[182:185], v[190:193], v[48:51]
	v_mfma_f32_16x16x32_bf16 v[40:43], v[174:177], v[198:201], v[40:43]
	v_mfma_f32_16x16x32_bf16 v[32:35], v[182:185], v[198:201], v[32:35]
	v_mfma_f32_16x16x32_bf16 v[24:27], v[174:177], v[206:209], v[24:27]
	v_mfma_f32_16x16x32_bf16 v[16:19], v[182:185], v[206:209], v[16:19]
	v_mfma_f32_16x16x32_bf16 v[8:11], v[174:177], v[214:217], v[8:11]
	v_mfma_f32_16x16x32_bf16 v[0:3], v[182:185], v[214:217], v[0:3]
	s_barrier
	s_setprio 0
	s_add_i32 s63, s63, 2
	s_add_u32 s28, s28, 0x100
	s_addc_u32 s29, s29, 0
	s_add_u32 s61, s61, 0x100
	s_addc_u32 s62, s62, 0
	s_cmp_gt_u32 s63, 13
	s_cbranch_scc0 .LBB0_555
	s_and_b64 vcc, exec, s[14:15]
	s_cbranch_vccz .LBB0_558
	s_barrier

.LBB0_637:
	s_add_u32 s22, s20, 0x100
	s_addc_u32 s23, s21, 0
	s_cmp_eq_u32 s61, 40
	s_cselect_b32 s27, s9, s23
	s_cselect_b32 s26, s8, s22
	s_cselect_b32 s25, s19, s60
	s_cselect_b32 s24, s18, s51
	s_add_u32 s98, s24, s14
	s_addc_u32 s99, s25, s15
	s_add_u32 s100, s26, s14
	s_addc_u32 s101, s27, s15
	s_add_i32 m0, s29, 0xc000
	s_nop 0
	global_load_lds_dwordx4 v200, s[20:21]
	s_add_i32 m0, s29, 0xe000
	s_nop 0
	global_load_lds_dwordx4 v202, s[20:21]
	ds_read_b128 v[120:123], v247
	ds_read_b128 v[124:127], v247 offset:1024
	ds_read_b128 v[128:131], v247 offset:2048
	ds_read_b128 v[132:135], v247 offset:3072
	ds_read_b128 v[140:143], v248
	ds_read_b128 v[148:151], v248 offset:1024
	ds_read_b128 v[152:155], v248 offset:2048
	ds_read_b128 v[156:159], v248 offset:3072
	ds_read_b128 v[160:163], v249
	ds_read_b128 v[164:167], v249 offset:1024
	ds_read_b128 v[168:171], v249 offset:2048
	ds_read_b128 v[172:175], v249 offset:3072
	ds_read_b128 v[176:179], v249 offset:4096
	ds_read_b128 v[180:183], v249 offset:5120
	ds_read_b128 v[184:187], v249 offset:6144
	ds_read_b128 v[188:191], v249 offset:7168
	s_waitcnt vmcnt(8)
	s_waitcnt lgkmcnt(0)
	s_setprio 1
	s_barrier
	v_mfma_f32_16x16x32_bf16 v[144:147], v[120:123], v[160:163], v[144:147]
	v_mfma_f32_16x16x32_bf16 v[136:139], v[128:131], v[160:163], v[136:139]
	v_mfma_f32_16x16x32_bf16 v[108:111], v[120:123], v[168:171], v[108:111]
	v_mfma_f32_16x16x32_bf16 v[104:107], v[128:131], v[168:171], v[104:107]
	v_mfma_f32_16x16x32_bf16 v[92:95], v[120:123], v[176:179], v[92:95]
	v_mfma_f32_16x16x32_bf16 v[88:91], v[128:131], v[176:179], v[88:91]
	v_mfma_f32_16x16x32_bf16 v[76:79], v[120:123], v[184:187], v[76:79]
	v_mfma_f32_16x16x32_bf16 v[72:75], v[128:131], v[184:187], v[72:75]
	v_mfma_f32_16x16x32_bf16 v[144:147], v[124:127], v[164:167], v[144:147]
	v_mfma_f32_16x16x32_bf16 v[136:139], v[132:135], v[164:167], v[136:139]
	v_mfma_f32_16x16x32_bf16 v[108:111], v[124:127], v[172:175], v[108:111]
	v_mfma_f32_16x16x32_bf16 v[104:107], v[132:135], v[172:175], v[104:107]
	v_mfma_f32_16x16x32_bf16 v[92:95], v[124:127], v[180:183], v[92:95]
	v_mfma_f32_16x16x32_bf16 v[88:91], v[132:135], v[180:183], v[88:91]
	v_mfma_f32_16x16x32_bf16 v[76:79], v[124:127], v[188:191], v[76:79]
	v_mfma_f32_16x16x32_bf16 v[72:75], v[132:135], v[188:191], v[72:75]
	s_setprio 0
	s_setprio 1
	v_mfma_f32_16x16x32_bf16 v[116:119], v[140:143], v[160:163], v[116:119]
	v_mfma_f32_16x16x32_bf16 v[112:115], v[152:155], v[160:163], v[112:115]
	v_mfma_f32_16x16x32_bf16 v[100:103], v[140:143], v[168:171], v[100:103]
	v_mfma_f32_16x16x32_bf16 v[96:99], v[152:155], v[168:171], v[96:99]
	v_mfma_f32_16x16x32_bf16 v[84:87], v[140:143], v[176:179], v[84:87]
	v_mfma_f32_16x16x32_bf16 v[80:83], v[152:155], v[176:179], v[80:83]
	v_mfma_f32_16x16x32_bf16 v[68:71], v[140:143], v[184:187], v[68:71]
	v_mfma_f32_16x16x32_bf16 v[64:67], v[152:155], v[184:187], v[64:67]
	v_mfma_f32_16x16x32_bf16 v[116:119], v[148:151], v[164:167], v[116:119]
	v_mfma_f32_16x16x32_bf16 v[112:115], v[156:159], v[164:167], v[112:115]
	v_mfma_f32_16x16x32_bf16 v[100:103], v[148:151], v[172:175], v[100:103]
	v_mfma_f32_16x16x32_bf16 v[96:99], v[156:159], v[172:175], v[96:99]
	v_mfma_f32_16x16x32_bf16 v[84:87], v[148:151], v[180:183], v[84:87]
	v_mfma_f32_16x16x32_bf16 v[80:83], v[156:159], v[180:183], v[80:83]
	v_mfma_f32_16x16x32_bf16 v[68:71], v[148:151], v[188:191], v[68:71]
	v_mfma_f32_16x16x32_bf16 v[64:67], v[156:159], v[188:191], v[64:67]
	s_barrier
	s_setprio 0
	s_add_i32 s20, s43, s28
	s_mov_b32 m0, s20
	s_nop 0
	global_load_lds_dwordx4 v194, s[24:25]
	s_add_i32 m0, s20, 0x2000
	s_add_u32 s20, s24, 0xb0000
	s_addc_u32 s21, s25, 0
	s_add_i32 s62, s46, s28
	global_load_lds_dwordx4 v198, s[24:25]
	s_mov_b32 m0, s62
	s_nop 0
	global_load_lds_dwordx4 v194, s[20:21]
	s_add_i32 m0, s62, 0x2000
	s_nop 0
	global_load_lds_dwordx4 v198, s[20:21]
	s_mov_b32 m0, s29
	s_nop 0
	global_load_lds_dwordx4 v192, s[26:27]
	s_mov_b32 m0, s30
	s_nop 0
	global_load_lds_dwordx4 v196, s[26:27]
	ds_read_b128 v[160:163], v249 offset:16384
	ds_read_b128 v[164:167], v249 offset:17408
	ds_read_b128 v[168:171], v249 offset:18432
	ds_read_b128 v[172:175], v249 offset:19456
	ds_read_b128 v[176:179], v249 offset:20480
	ds_read_b128 v[180:183], v249 offset:21504
	ds_read_b128 v[184:187], v249 offset:22528
	ds_read_b128 v[188:191], v249 offset:23552
	s_waitcnt vmcnt(8)
	s_waitcnt lgkmcnt(0)
	s_setprio 1
	s_barrier
	v_mfma_f32_16x16x32_bf16 v[60:63], v[120:123], v[160:163], v[60:63]
	v_mfma_f32_16x16x32_bf16 v[56:59], v[128:131], v[160:163], v[56:59]
	v_mfma_f32_16x16x32_bf16 v[44:47], v[120:123], v[168:171], v[44:47]
	v_mfma_f32_16x16x32_bf16 v[40:43], v[128:131], v[168:171], v[40:43]
	v_mfma_f32_16x16x32_bf16 v[28:31], v[120:123], v[176:179], v[28:31]
	v_mfma_f32_16x16x32_bf16 v[24:27], v[128:131], v[176:179], v[24:27]
	v_mfma_f32_16x16x32_bf16 v[12:15], v[120:123], v[184:187], v[12:15]
	v_mfma_f32_16x16x32_bf16 v[8:11], v[128:131], v[184:187], v[8:11]
	v_mfma_f32_16x16x32_bf16 v[60:63], v[124:127], v[164:167], v[60:63]
	v_mfma_f32_16x16x32_bf16 v[56:59], v[132:135], v[164:167], v[56:59]
	v_mfma_f32_16x16x32_bf16 v[44:47], v[124:127], v[172:175], v[44:47]
	v_mfma_f32_16x16x32_bf16 v[40:43], v[132:135], v[172:175], v[40:43]
	v_mfma_f32_16x16x32_bf16 v[28:31], v[124:127], v[180:183], v[28:31]
	v_mfma_f32_16x16x32_bf16 v[24:27], v[132:135], v[180:183], v[24:27]
	v_mfma_f32_16x16x32_bf16 v[12:15], v[124:127], v[188:191], v[12:15]
	v_mfma_f32_16x16x32_bf16 v[8:11], v[132:135], v[188:191], v[8:11]
	s_setprio 0
	s_setprio 1
	v_mfma_f32_16x16x32_bf16 v[52:55], v[140:143], v[160:163], v[52:55]
	v_mfma_f32_16x16x32_bf16 v[48:51], v[152:155], v[160:163], v[48:51]
	v_mfma_f32_16x16x32_bf16 v[36:39], v[140:143], v[168:171], v[36:39]
	v_mfma_f32_16x16x32_bf16 v[32:35], v[152:155], v[168:171], v[32:35]
	v_mfma_f32_16x16x32_bf16 v[20:23], v[140:143], v[176:179], v[20:23]
	v_mfma_f32_16x16x32_bf16 v[16:19], v[152:155], v[176:179], v[16:19]
	v_mfma_f32_16x16x32_bf16 v[4:7], v[140:143], v[184:187], v[4:7]
	v_mfma_f32_16x16x32_bf16 v[0:3], v[152:155], v[184:187], v[0:3]
	v_mfma_f32_16x16x32_bf16 v[52:55], v[148:151], v[164:167], v[52:55]
	v_mfma_f32_16x16x32_bf16 v[48:51], v[156:159], v[164:167], v[48:51]
	v_mfma_f32_16x16x32_bf16 v[36:39], v[148:151], v[172:175], v[36:39]
	v_mfma_f32_16x16x32_bf16 v[32:35], v[156:159], v[172:175], v[32:35]
	v_mfma_f32_16x16x32_bf16 v[20:23], v[148:151], v[180:183], v[20:23]
	v_mfma_f32_16x16x32_bf16 v[16:19], v[156:159], v[180:183], v[16:19]
	v_mfma_f32_16x16x32_bf16 v[4:7], v[148:151], v[188:191], v[4:7]
	v_mfma_f32_16x16x32_bf16 v[0:3], v[156:159], v[188:191], v[0:3]
	s_barrier
	s_setprio 0
	s_add_i32 s62, 0, 0x18000
	s_add_i32 s63, 0, 0x1c000
	s_add_u32 s20, s26, 0xb0000
	s_addc_u32 s21, s27, 0
	s_mov_b32 m0, s31
	s_nop 0
	global_load_lds_dwordx4 v192, s[20:21]
	s_mov_b32 m0, s34
	s_nop 0
	global_load_lds_dwordx4 v196, s[20:21]
	v_add_u32_e32 v132, s62, v246
	v_add_u32_e32 v156, s63, v246
	ds_read_b128 v[120:123], v132
	ds_read_b128 v[124:127], v132 offset:1024
	ds_read_b128 v[128:131], v132 offset:2048
	ds_read_b128 v[132:135], v132 offset:3072
	ds_read_b128 v[140:143], v156
	ds_read_b128 v[148:151], v156 offset:1024
	ds_read_b128 v[152:155], v156 offset:2048
	ds_read_b128 v[156:159], v156 offset:3072
	ds_read_b128 v[160:163], v249 offset:32768
	ds_read_b128 v[164:167], v249 offset:33792
	ds_read_b128 v[168:171], v249 offset:34816
	ds_read_b128 v[172:175], v249 offset:35840
	ds_read_b128 v[176:179], v249 offset:36864
	ds_read_b128 v[180:183], v249 offset:37888
	ds_read_b128 v[184:187], v249 offset:38912
	ds_read_b128 v[188:191], v249 offset:39936
	s_waitcnt vmcnt(8)
	s_waitcnt lgkmcnt(0)
	s_setprio 1
	s_barrier
	v_mfma_f32_16x16x32_bf16 v[144:147], v[120:123], v[160:163], v[144:147]
	v_mfma_f32_16x16x32_bf16 v[136:139], v[128:131], v[160:163], v[136:139]
	v_mfma_f32_16x16x32_bf16 v[108:111], v[120:123], v[168:171], v[108:111]
	v_mfma_f32_16x16x32_bf16 v[104:107], v[128:131], v[168:171], v[104:107]
	v_mfma_f32_16x16x32_bf16 v[92:95], v[120:123], v[176:179], v[92:95]
	v_mfma_f32_16x16x32_bf16 v[88:91], v[128:131], v[176:179], v[88:91]
	v_mfma_f32_16x16x32_bf16 v[76:79], v[120:123], v[184:187], v[76:79]
	v_mfma_f32_16x16x32_bf16 v[72:75], v[128:131], v[184:187], v[72:75]
	v_mfma_f32_16x16x32_bf16 v[144:147], v[124:127], v[164:167], v[144:147]
	v_mfma_f32_16x16x32_bf16 v[136:139], v[132:135], v[164:167], v[136:139]
	v_mfma_f32_16x16x32_bf16 v[108:111], v[124:127], v[172:175], v[108:111]
	v_mfma_f32_16x16x32_bf16 v[104:107], v[132:135], v[172:175], v[104:107]
	v_mfma_f32_16x16x32_bf16 v[92:95], v[124:127], v[180:183], v[92:95]
	v_mfma_f32_16x16x32_bf16 v[88:91], v[132:135], v[180:183], v[88:91]
	v_mfma_f32_16x16x32_bf16 v[76:79], v[124:127], v[188:191], v[76:79]
	v_mfma_f32_16x16x32_bf16 v[72:75], v[132:135], v[188:191], v[72:75]
	s_setprio 0
	s_setprio 1
	v_mfma_f32_16x16x32_bf16 v[116:119], v[140:143], v[160:163], v[116:119]
	v_mfma_f32_16x16x32_bf16 v[112:115], v[152:155], v[160:163], v[112:115]
	v_mfma_f32_16x16x32_bf16 v[100:103], v[140:143], v[168:171], v[100:103]
	v_mfma_f32_16x16x32_bf16 v[96:99], v[152:155], v[168:171], v[96:99]
	v_mfma_f32_16x16x32_bf16 v[84:87], v[140:143], v[176:179], v[84:87]
	v_mfma_f32_16x16x32_bf16 v[80:83], v[152:155], v[176:179], v[80:83]
	v_mfma_f32_16x16x32_bf16 v[68:71], v[140:143], v[184:187], v[68:71]
	v_mfma_f32_16x16x32_bf16 v[64:67], v[152:155], v[184:187], v[64:67]
	v_mfma_f32_16x16x32_bf16 v[116:119], v[148:151], v[164:167], v[116:119]
	v_mfma_f32_16x16x32_bf16 v[112:115], v[156:159], v[164:167], v[112:115]
	v_mfma_f32_16x16x32_bf16 v[100:103], v[148:151], v[172:175], v[100:103]
	v_mfma_f32_16x16x32_bf16 v[96:99], v[156:159], v[172:175], v[96:99]
	v_mfma_f32_16x16x32_bf16 v[84:87], v[148:151], v[180:183], v[84:87]
	v_mfma_f32_16x16x32_bf16 v[80:83], v[156:159], v[180:183], v[80:83]
	v_mfma_f32_16x16x32_bf16 v[68:71], v[148:151], v[188:191], v[68:71]
	v_mfma_f32_16x16x32_bf16 v[64:67], v[156:159], v[188:191], v[64:67]
	s_barrier
	s_setprio 0
	s_add_i32 s20, s62, s28
	s_mov_b32 m0, s20
	s_nop 0
	global_load_lds_dwordx4 v194, s[98:99]
	s_add_i32 m0, s20, 0x2000
	s_add_u32 s20, s24, 0xb0080
	s_addc_u32 s21, s25, 0
	s_add_i32 s24, s63, s28
	global_load_lds_dwordx4 v198, s[98:99]
	s_mov_b32 m0, s24
	s_nop 0
	global_load_lds_dwordx4 v194, s[20:21]
	s_add_i32 m0, s24, 0x2000
	s_nop 0
	global_load_lds_dwordx4 v198, s[20:21]
	s_mov_b32 m0, s38
	s_nop 0
	global_load_lds_dwordx4 v192, s[100:101]
	s_mov_b32 m0, s39
	s_nop 0
	global_load_lds_dwordx4 v196, s[100:101]
	ds_read_b128 v[160:163], v249 offset:49152
	ds_read_b128 v[164:167], v249 offset:50176
	ds_read_b128 v[168:171], v249 offset:51200
	ds_read_b128 v[172:175], v249 offset:52224
	ds_read_b128 v[176:179], v249 offset:53248
	ds_read_b128 v[180:183], v249 offset:54272
	ds_read_b128 v[184:187], v249 offset:55296
	ds_read_b128 v[188:191], v249 offset:56320
	s_waitcnt vmcnt(8)
	s_waitcnt lgkmcnt(0)
	s_setprio 1
	s_barrier
	v_mfma_f32_16x16x32_bf16 v[60:63], v[120:123], v[160:163], v[60:63]
	v_mfma_f32_16x16x32_bf16 v[56:59], v[128:131], v[160:163], v[56:59]
	v_mfma_f32_16x16x32_bf16 v[44:47], v[120:123], v[168:171], v[44:47]
	v_mfma_f32_16x16x32_bf16 v[40:43], v[128:131], v[168:171], v[40:43]
	v_mfma_f32_16x16x32_bf16 v[28:31], v[120:123], v[176:179], v[28:31]
	v_mfma_f32_16x16x32_bf16 v[24:27], v[128:131], v[176:179], v[24:27]
	v_mfma_f32_16x16x32_bf16 v[12:15], v[120:123], v[184:187], v[12:15]
	v_mfma_f32_16x16x32_bf16 v[8:11], v[128:131], v[184:187], v[8:11]
	v_mfma_f32_16x16x32_bf16 v[60:63], v[124:127], v[164:167], v[60:63]
	v_mfma_f32_16x16x32_bf16 v[56:59], v[132:135], v[164:167], v[56:59]
	v_mfma_f32_16x16x32_bf16 v[44:47], v[124:127], v[172:175], v[44:47]
	v_mfma_f32_16x16x32_bf16 v[40:43], v[132:135], v[172:175], v[40:43]
	v_mfma_f32_16x16x32_bf16 v[28:31], v[124:127], v[180:183], v[28:31]
	v_mfma_f32_16x16x32_bf16 v[24:27], v[132:135], v[180:183], v[24:27]
	v_mfma_f32_16x16x32_bf16 v[12:15], v[124:127], v[188:191], v[12:15]
	v_mfma_f32_16x16x32_bf16 v[8:11], v[132:135], v[188:191], v[8:11]
	s_setprio 0
	s_setprio 1
	v_mfma_f32_16x16x32_bf16 v[52:55], v[140:143], v[160:163], v[52:55]
	v_mfma_f32_16x16x32_bf16 v[48:51], v[152:155], v[160:163], v[48:51]
	v_mfma_f32_16x16x32_bf16 v[36:39], v[140:143], v[168:171], v[36:39]
	v_mfma_f32_16x16x32_bf16 v[32:35], v[152:155], v[168:171], v[32:35]
	v_mfma_f32_16x16x32_bf16 v[20:23], v[140:143], v[176:179], v[20:23]
	v_mfma_f32_16x16x32_bf16 v[16:19], v[152:155], v[176:179], v[16:19]
	v_mfma_f32_16x16x32_bf16 v[4:7], v[140:143], v[184:187], v[4:7]
	v_mfma_f32_16x16x32_bf16 v[0:3], v[152:155], v[184:187], v[0:3]
	v_mfma_f32_16x16x32_bf16 v[52:55], v[148:151], v[164:167], v[52:55]
	v_mfma_f32_16x16x32_bf16 v[48:51], v[156:159], v[164:167], v[48:51]
	v_mfma_f32_16x16x32_bf16 v[36:39], v[148:151], v[172:175], v[36:39]
	v_mfma_f32_16x16x32_bf16 v[32:35], v[156:159], v[172:175], v[32:35]
	v_mfma_f32_16x16x32_bf16 v[20:23], v[148:151], v[180:183], v[20:23]
	v_mfma_f32_16x16x32_bf16 v[16:19], v[156:159], v[180:183], v[16:19]
	v_mfma_f32_16x16x32_bf16 v[4:7], v[148:151], v[188:191], v[4:7]
	v_mfma_f32_16x16x32_bf16 v[0:3], v[156:159], v[188:191], v[0:3]
	s_barrier
	s_setprio 0
	s_add_i32 s61, s61, 2
	s_add_u32 s51, s51, 0x100
	s_addc_u32 s60, s60, 0
	s_cmp_gt_u32 s61, 41
	s_mov_b64 s[20:21], s[22:23]
	s_cbranch_scc0 .LBB0_637
	s_and_b64 vcc, exec, s[16:17]
	s_cbranch_vccz .LBB0_640
	s_barrier

.LBB0_723:
	s_add_u32 s62, s48, 0xfffc0080
	s_addc_u32 s63, s49, -1
	s_cmp_eq_u32 s93, 12
	s_cselect_b32 s65, s9, s63
	s_cselect_b32 s64, s41, s62
	s_cselect_b32 s63, s39, s61
	s_cselect_b32 s62, s51, s60
	s_add_u32 s98, s62, s14
	s_addc_u32 s99, s63, s15
	s_add_u32 s100, s64, s14
	s_addc_u32 s101, s65, s15
	s_add_i32 m0, s69, 0xc000
	s_nop 0
	global_load_lds_dwordx4 v214, s[48:49]
	s_add_i32 m0, s69, 0xe000
	s_nop 0
	global_load_lds_dwordx4 v216, s[48:49]
	ds_read_b128 v[128:131], v235
	ds_read_b128 v[132:135], v235 offset:1024
	ds_read_b128 v[136:139], v235 offset:2048
	ds_read_b128 v[140:143], v235 offset:3072
	ds_read_b128 v[144:147], v236
	ds_read_b128 v[148:151], v236 offset:1024
	ds_read_b128 v[152:155], v236 offset:2048
	ds_read_b128 v[156:159], v236 offset:3072
	ds_read_b128 v[160:163], v237
	ds_read_b128 v[164:167], v237 offset:1024
	ds_read_b128 v[168:171], v237 offset:2048
	ds_read_b128 v[172:175], v237 offset:3072
	ds_read_b128 v[176:179], v237 offset:4096
	ds_read_b128 v[180:183], v237 offset:5120
	ds_read_b128 v[184:187], v237 offset:6144
	ds_read_b128 v[188:191], v237 offset:7168
	s_waitcnt vmcnt(8)
	s_waitcnt lgkmcnt(0)
	s_setprio 1
	s_barrier
	v_mfma_f32_16x16x32_bf16 v[124:127], v[128:131], v[160:163], v[124:127]
	v_mfma_f32_16x16x32_bf16 v[120:123], v[136:139], v[160:163], v[120:123]
	v_mfma_f32_16x16x32_bf16 v[116:119], v[128:131], v[168:171], v[116:119]
	v_mfma_f32_16x16x32_bf16 v[112:115], v[136:139], v[168:171], v[112:115]
	v_mfma_f32_16x16x32_bf16 v[108:111], v[128:131], v[176:179], v[108:111]
	v_mfma_f32_16x16x32_bf16 v[100:103], v[136:139], v[176:179], v[100:103]
	v_mfma_f32_16x16x32_bf16 v[92:95], v[128:131], v[184:187], v[92:95]
	v_mfma_f32_16x16x32_bf16 v[80:83], v[136:139], v[184:187], v[80:83]
	v_mfma_f32_16x16x32_bf16 v[124:127], v[132:135], v[164:167], v[124:127]
	v_mfma_f32_16x16x32_bf16 v[120:123], v[140:143], v[164:167], v[120:123]
	v_mfma_f32_16x16x32_bf16 v[116:119], v[132:135], v[172:175], v[116:119]
	v_mfma_f32_16x16x32_bf16 v[112:115], v[140:143], v[172:175], v[112:115]
	v_mfma_f32_16x16x32_bf16 v[108:111], v[132:135], v[180:183], v[108:111]
	v_mfma_f32_16x16x32_bf16 v[100:103], v[140:143], v[180:183], v[100:103]
	v_mfma_f32_16x16x32_bf16 v[92:95], v[132:135], v[188:191], v[92:95]
	v_mfma_f32_16x16x32_bf16 v[80:83], v[140:143], v[188:191], v[80:83]
	s_setprio 0
	s_setprio 1
	v_mfma_f32_16x16x32_bf16 v[104:107], v[144:147], v[160:163], v[104:107]
	v_mfma_f32_16x16x32_bf16 v[96:99], v[152:155], v[160:163], v[96:99]
	v_mfma_f32_16x16x32_bf16 v[88:91], v[144:147], v[168:171], v[88:91]
	v_mfma_f32_16x16x32_bf16 v[84:87], v[152:155], v[168:171], v[84:87]
	v_mfma_f32_16x16x32_bf16 v[76:79], v[144:147], v[176:179], v[76:79]
	v_mfma_f32_16x16x32_bf16 v[72:75], v[152:155], v[176:179], v[72:75]
	v_mfma_f32_16x16x32_bf16 v[68:71], v[144:147], v[184:187], v[68:71]
	v_mfma_f32_16x16x32_bf16 v[64:67], v[152:155], v[184:187], v[64:67]
	v_mfma_f32_16x16x32_bf16 v[104:107], v[148:151], v[164:167], v[104:107]
	v_mfma_f32_16x16x32_bf16 v[96:99], v[156:159], v[164:167], v[96:99]
	v_mfma_f32_16x16x32_bf16 v[88:91], v[148:151], v[172:175], v[88:91]
	v_mfma_f32_16x16x32_bf16 v[84:87], v[156:159], v[172:175], v[84:87]
	v_mfma_f32_16x16x32_bf16 v[76:79], v[148:151], v[180:183], v[76:79]
	v_mfma_f32_16x16x32_bf16 v[72:75], v[156:159], v[180:183], v[72:75]
	v_mfma_f32_16x16x32_bf16 v[68:71], v[148:151], v[188:191], v[68:71]
	v_mfma_f32_16x16x32_bf16 v[64:67], v[156:159], v[188:191], v[64:67]
	s_barrier
	s_setprio 0
	s_add_i32 s94, s88, s68
	s_mov_b32 m0, s94
	s_nop 0
	global_load_lds_dwordx4 v208, s[62:63]
	s_add_i32 m0, s94, 0x2000
	s_add_u32 s94, s62, 0x40000
	s_addc_u32 s95, s63, 0
	s_add_i32 s96, s89, s68
	global_load_lds_dwordx4 v212, s[62:63]
	s_mov_b32 m0, s96
	s_nop 0
	global_load_lds_dwordx4 v208, s[94:95]
	s_add_i32 m0, s96, 0x2000
	s_nop 0
	global_load_lds_dwordx4 v212, s[94:95]
	s_mov_b32 m0, s69
	s_nop 0
	global_load_lds_dwordx4 v206, s[64:65]
	s_mov_b32 m0, s70
	s_nop 0
	global_load_lds_dwordx4 v210, s[64:65]
	ds_read_b128 v[160:163], v237 offset:16384
	ds_read_b128 v[164:167], v237 offset:17408
	ds_read_b128 v[168:171], v237 offset:18432
	ds_read_b128 v[172:175], v237 offset:19456
	ds_read_b128 v[176:179], v237 offset:20480
	ds_read_b128 v[180:183], v237 offset:21504
	ds_read_b128 v[184:187], v237 offset:22528
	ds_read_b128 v[188:191], v237 offset:23552
	s_waitcnt vmcnt(8)
	s_waitcnt lgkmcnt(0)
	s_setprio 1
	s_barrier
	v_mfma_f32_16x16x32_bf16 v[60:63], v[128:131], v[160:163], v[60:63]
	v_mfma_f32_16x16x32_bf16 v[56:59], v[136:139], v[160:163], v[56:59]
	v_mfma_f32_16x16x32_bf16 v[48:51], v[128:131], v[168:171], v[48:51]
	v_mfma_f32_16x16x32_bf16 v[40:43], v[136:139], v[168:171], v[40:43]
	v_mfma_f32_16x16x32_bf16 v[32:35], v[128:131], v[176:179], v[32:35]
	v_mfma_f32_16x16x32_bf16 v[24:27], v[136:139], v[176:179], v[24:27]
	v_mfma_f32_16x16x32_bf16 v[16:19], v[128:131], v[184:187], v[16:19]
	v_mfma_f32_16x16x32_bf16 v[8:11], v[136:139], v[184:187], v[8:11]
	v_mfma_f32_16x16x32_bf16 v[60:63], v[132:135], v[164:167], v[60:63]
	v_mfma_f32_16x16x32_bf16 v[56:59], v[140:143], v[164:167], v[56:59]
	v_mfma_f32_16x16x32_bf16 v[48:51], v[132:135], v[172:175], v[48:51]
	v_mfma_f32_16x16x32_bf16 v[40:43], v[140:143], v[172:175], v[40:43]
	v_mfma_f32_16x16x32_bf16 v[32:35], v[132:135], v[180:183], v[32:35]
	v_mfma_f32_16x16x32_bf16 v[24:27], v[140:143], v[180:183], v[24:27]
	v_mfma_f32_16x16x32_bf16 v[16:19], v[132:135], v[188:191], v[16:19]
	v_mfma_f32_16x16x32_bf16 v[8:11], v[140:143], v[188:191], v[8:11]
	s_setprio 0
	s_setprio 1
	v_mfma_f32_16x16x32_bf16 v[52:55], v[144:147], v[160:163], v[52:55]
	v_mfma_f32_16x16x32_bf16 v[44:47], v[152:155], v[160:163], v[44:47]
	v_mfma_f32_16x16x32_bf16 v[36:39], v[144:147], v[168:171], v[36:39]
	v_mfma_f32_16x16x32_bf16 v[28:31], v[152:155], v[168:171], v[28:31]
	v_mfma_f32_16x16x32_bf16 v[20:23], v[144:147], v[176:179], v[20:23]
	v_mfma_f32_16x16x32_bf16 v[12:15], v[152:155], v[176:179], v[12:15]
	v_mfma_f32_16x16x32_bf16 v[4:7], v[144:147], v[184:187], v[4:7]
	v_mfma_f32_16x16x32_bf16 v[0:3], v[152:155], v[184:187], v[0:3]
	v_mfma_f32_16x16x32_bf16 v[52:55], v[148:151], v[164:167], v[52:55]
	v_mfma_f32_16x16x32_bf16 v[44:47], v[156:159], v[164:167], v[44:47]
	v_mfma_f32_16x16x32_bf16 v[36:39], v[148:151], v[172:175], v[36:39]
	v_mfma_f32_16x16x32_bf16 v[28:31], v[156:159], v[172:175], v[28:31]
	v_mfma_f32_16x16x32_bf16 v[20:23], v[148:151], v[180:183], v[20:23]
	v_mfma_f32_16x16x32_bf16 v[12:15], v[156:159], v[180:183], v[12:15]
	v_mfma_f32_16x16x32_bf16 v[4:7], v[148:151], v[188:191], v[4:7]
	v_mfma_f32_16x16x32_bf16 v[0:3], v[156:159], v[188:191], v[0:3]
	s_barrier
	s_setprio 0
	s_add_i32 s94, 0, 0x18000
	s_add_i32 s95, 0, 0x1c000
	s_add_u32 s64, s64, 0x40000
	s_addc_u32 s65, s65, 0
	s_mov_b32 m0, s71
	s_nop 0
	global_load_lds_dwordx4 v206, s[64:65]
	s_mov_b32 m0, s72
	s_nop 0
	global_load_lds_dwordx4 v210, s[64:65]
	v_add_u32_e32 v140, s94, v234
	v_add_u32_e32 v156, s95, v234
	ds_read_b128 v[128:131], v140
	ds_read_b128 v[132:135], v140 offset:1024
	ds_read_b128 v[136:139], v140 offset:2048
	ds_read_b128 v[140:143], v140 offset:3072
	ds_read_b128 v[144:147], v156
	ds_read_b128 v[148:151], v156 offset:1024
	ds_read_b128 v[152:155], v156 offset:2048
	ds_read_b128 v[156:159], v156 offset:3072
	ds_read_b128 v[160:163], v237 offset:32768
	ds_read_b128 v[164:167], v237 offset:33792
	ds_read_b128 v[168:171], v237 offset:34816
	ds_read_b128 v[172:175], v237 offset:35840
	ds_read_b128 v[176:179], v237 offset:36864
	ds_read_b128 v[180:183], v237 offset:37888
	ds_read_b128 v[184:187], v237 offset:38912
	ds_read_b128 v[188:191], v237 offset:39936
	s_waitcnt vmcnt(8)
	s_waitcnt lgkmcnt(0)
	s_setprio 1
	s_barrier
	v_mfma_f32_16x16x32_bf16 v[124:127], v[128:131], v[160:163], v[124:127]
	v_mfma_f32_16x16x32_bf16 v[120:123], v[136:139], v[160:163], v[120:123]
	v_mfma_f32_16x16x32_bf16 v[116:119], v[128:131], v[168:171], v[116:119]
	v_mfma_f32_16x16x32_bf16 v[112:115], v[136:139], v[168:171], v[112:115]
	v_mfma_f32_16x16x32_bf16 v[108:111], v[128:131], v[176:179], v[108:111]
	v_mfma_f32_16x16x32_bf16 v[100:103], v[136:139], v[176:179], v[100:103]
	v_mfma_f32_16x16x32_bf16 v[92:95], v[128:131], v[184:187], v[92:95]
	v_mfma_f32_16x16x32_bf16 v[80:83], v[136:139], v[184:187], v[80:83]
	v_mfma_f32_16x16x32_bf16 v[124:127], v[132:135], v[164:167], v[124:127]
	v_mfma_f32_16x16x32_bf16 v[120:123], v[140:143], v[164:167], v[120:123]
	v_mfma_f32_16x16x32_bf16 v[116:119], v[132:135], v[172:175], v[116:119]
	v_mfma_f32_16x16x32_bf16 v[112:115], v[140:143], v[172:175], v[112:115]
	v_mfma_f32_16x16x32_bf16 v[108:111], v[132:135], v[180:183], v[108:111]
	v_mfma_f32_16x16x32_bf16 v[100:103], v[140:143], v[180:183], v[100:103]
	v_mfma_f32_16x16x32_bf16 v[92:95], v[132:135], v[188:191], v[92:95]
	v_mfma_f32_16x16x32_bf16 v[80:83], v[140:143], v[188:191], v[80:83]
	s_setprio 0
	s_setprio 1
	v_mfma_f32_16x16x32_bf16 v[104:107], v[144:147], v[160:163], v[104:107]
	v_mfma_f32_16x16x32_bf16 v[96:99], v[152:155], v[160:163], v[96:99]
	v_mfma_f32_16x16x32_bf16 v[88:91], v[144:147], v[168:171], v[88:91]
	v_mfma_f32_16x16x32_bf16 v[84:87], v[152:155], v[168:171], v[84:87]
	v_mfma_f32_16x16x32_bf16 v[76:79], v[144:147], v[176:179], v[76:79]
	v_mfma_f32_16x16x32_bf16 v[72:75], v[152:155], v[176:179], v[72:75]
	v_mfma_f32_16x16x32_bf16 v[68:71], v[144:147], v[184:187], v[68:71]
	v_mfma_f32_16x16x32_bf16 v[64:67], v[152:155], v[184:187], v[64:67]
	v_mfma_f32_16x16x32_bf16 v[104:107], v[148:151], v[164:167], v[104:107]
	v_mfma_f32_16x16x32_bf16 v[96:99], v[156:159], v[164:167], v[96:99]
	v_mfma_f32_16x16x32_bf16 v[88:91], v[148:151], v[172:175], v[88:91]
	v_mfma_f32_16x16x32_bf16 v[84:87], v[156:159], v[172:175], v[84:87]
	v_mfma_f32_16x16x32_bf16 v[76:79], v[148:151], v[180:183], v[76:79]
	v_mfma_f32_16x16x32_bf16 v[72:75], v[156:159], v[180:183], v[72:75]
	v_mfma_f32_16x16x32_bf16 v[68:71], v[148:151], v[188:191], v[68:71]
	v_mfma_f32_16x16x32_bf16 v[64:67], v[156:159], v[188:191], v[64:67]
	s_barrier
	s_setprio 0
	s_add_i32 s64, s94, s68
	s_mov_b32 m0, s64
	s_nop 0
	global_load_lds_dwordx4 v208, s[98:99]
	s_add_i32 m0, s64, 0x2000
	s_add_u32 s62, s62, 0x40080
	s_addc_u32 s63, s63, 0
	s_add_i32 s64, s95, s68
	global_load_lds_dwordx4 v212, s[98:99]
	s_mov_b32 m0, s64
	s_nop 0
	global_load_lds_dwordx4 v208, s[62:63]
	s_add_i32 m0, s64, 0x2000
	s_nop 0
	global_load_lds_dwordx4 v212, s[62:63]
	s_mov_b32 m0, s76
	s_nop 0
	global_load_lds_dwordx4 v206, s[100:101]
	s_mov_b32 m0, s77
	s_nop 0
	global_load_lds_dwordx4 v210, s[100:101]
	ds_read_b128 v[160:163], v237 offset:49152
	ds_read_b128 v[164:167], v237 offset:50176
	ds_read_b128 v[168:171], v237 offset:51200
	ds_read_b128 v[172:175], v237 offset:52224
	ds_read_b128 v[176:179], v237 offset:53248
	ds_read_b128 v[180:183], v237 offset:54272
	ds_read_b128 v[184:187], v237 offset:55296
	ds_read_b128 v[188:191], v237 offset:56320
	s_waitcnt vmcnt(8)
	s_waitcnt lgkmcnt(0)
	s_setprio 1
	s_barrier
	v_mfma_f32_16x16x32_bf16 v[60:63], v[128:131], v[160:163], v[60:63]
	v_mfma_f32_16x16x32_bf16 v[56:59], v[136:139], v[160:163], v[56:59]
	v_mfma_f32_16x16x32_bf16 v[48:51], v[128:131], v[168:171], v[48:51]
	v_mfma_f32_16x16x32_bf16 v[40:43], v[136:139], v[168:171], v[40:43]
	v_mfma_f32_16x16x32_bf16 v[32:35], v[128:131], v[176:179], v[32:35]
	v_mfma_f32_16x16x32_bf16 v[24:27], v[136:139], v[176:179], v[24:27]
	v_mfma_f32_16x16x32_bf16 v[16:19], v[128:131], v[184:187], v[16:19]
	v_mfma_f32_16x16x32_bf16 v[8:11], v[136:139], v[184:187], v[8:11]
	v_mfma_f32_16x16x32_bf16 v[60:63], v[132:135], v[164:167], v[60:63]
	v_mfma_f32_16x16x32_bf16 v[56:59], v[140:143], v[164:167], v[56:59]
	v_mfma_f32_16x16x32_bf16 v[48:51], v[132:135], v[172:175], v[48:51]
	v_mfma_f32_16x16x32_bf16 v[40:43], v[140:143], v[172:175], v[40:43]
	v_mfma_f32_16x16x32_bf16 v[32:35], v[132:135], v[180:183], v[32:35]
	v_mfma_f32_16x16x32_bf16 v[24:27], v[140:143], v[180:183], v[24:27]
	v_mfma_f32_16x16x32_bf16 v[16:19], v[132:135], v[188:191], v[16:19]
	v_mfma_f32_16x16x32_bf16 v[8:11], v[140:143], v[188:191], v[8:11]
	s_setprio 0
	s_setprio 1
	v_mfma_f32_16x16x32_bf16 v[52:55], v[144:147], v[160:163], v[52:55]
	v_mfma_f32_16x16x32_bf16 v[44:47], v[152:155], v[160:163], v[44:47]
	v_mfma_f32_16x16x32_bf16 v[36:39], v[144:147], v[168:171], v[36:39]
	v_mfma_f32_16x16x32_bf16 v[28:31], v[152:155], v[168:171], v[28:31]
	v_mfma_f32_16x16x32_bf16 v[20:23], v[144:147], v[176:179], v[20:23]
	v_mfma_f32_16x16x32_bf16 v[12:15], v[152:155], v[176:179], v[12:15]
	v_mfma_f32_16x16x32_bf16 v[4:7], v[144:147], v[184:187], v[4:7]
	v_mfma_f32_16x16x32_bf16 v[0:3], v[152:155], v[184:187], v[0:3]
	v_mfma_f32_16x16x32_bf16 v[52:55], v[148:151], v[164:167], v[52:55]
	v_mfma_f32_16x16x32_bf16 v[44:47], v[156:159], v[164:167], v[44:47]
	v_mfma_f32_16x16x32_bf16 v[36:39], v[148:151], v[172:175], v[36:39]
	v_mfma_f32_16x16x32_bf16 v[28:31], v[156:159], v[172:175], v[28:31]
	v_mfma_f32_16x16x32_bf16 v[20:23], v[148:151], v[180:183], v[20:23]
	v_mfma_f32_16x16x32_bf16 v[12:15], v[156:159], v[180:183], v[12:15]
	v_mfma_f32_16x16x32_bf16 v[4:7], v[148:151], v[188:191], v[4:7]
	v_mfma_f32_16x16x32_bf16 v[0:3], v[156:159], v[188:191], v[0:3]
	s_barrier
	s_setprio 0
	s_add_i32 s93, s93, 2
	s_add_u32 s48, s48, 0x100
	s_addc_u32 s49, s49, 0
	s_add_u32 s60, s60, 0x100
	s_addc_u32 s61, s61, 0
	s_cmp_gt_u32 s93, 13
	s_cbranch_scc0 .LBB0_723
	s_and_b64 vcc, exec, s[16:17]
	s_cbranch_vccz .LBB0_726
	s_barrier

.LBB0_1109:
	s_add_u32 s30, s28, 0xfffc0080
	s_addc_u32 s31, s29, -1
	s_cmp_eq_u32 s64, 12
	s_cselect_b32 s35, s19, s31
	s_cselect_b32 s34, s25, s30
	s_cselect_b32 s31, s17, s63
	s_cselect_b32 s30, s61, s62
	s_add_u32 s98, s30, s12
	s_addc_u32 s99, s31, s13
	s_add_u32 s100, s34, s12
	s_addc_u32 s101, s35, s13
	s_add_i32 m0, s27, 0xc000
	s_nop 0
	global_load_lds_dwordx4 v200, s[28:29]
	s_add_i32 m0, s27, 0xe000
	s_nop 0
	global_load_lds_dwordx4 v202, s[28:29]
	ds_read_b128 v[120:123], v246
	ds_read_b128 v[124:127], v246 offset:1024
	ds_read_b128 v[128:131], v246 offset:2048
	ds_read_b128 v[132:135], v246 offset:3072
	ds_read_b128 v[140:143], v247
	ds_read_b128 v[148:151], v247 offset:1024
	ds_read_b128 v[152:155], v247 offset:2048
	ds_read_b128 v[156:159], v247 offset:3072
	ds_read_b128 v[160:163], v248
	ds_read_b128 v[164:167], v248 offset:1024
	ds_read_b128 v[168:171], v248 offset:2048
	ds_read_b128 v[172:175], v248 offset:3072
	ds_read_b128 v[176:179], v248 offset:4096
	ds_read_b128 v[180:183], v248 offset:5120
	ds_read_b128 v[184:187], v248 offset:6144
	ds_read_b128 v[188:191], v248 offset:7168
	s_waitcnt vmcnt(8)
	s_waitcnt lgkmcnt(0)
	s_setprio 1
	s_barrier
	v_mfma_f32_16x16x32_bf16 v[144:147], v[120:123], v[160:163], v[144:147]
	v_mfma_f32_16x16x32_bf16 v[136:139], v[128:131], v[160:163], v[136:139]
	v_mfma_f32_16x16x32_bf16 v[108:111], v[120:123], v[168:171], v[108:111]
	v_mfma_f32_16x16x32_bf16 v[104:107], v[128:131], v[168:171], v[104:107]
	v_mfma_f32_16x16x32_bf16 v[92:95], v[120:123], v[176:179], v[92:95]
	v_mfma_f32_16x16x32_bf16 v[88:91], v[128:131], v[176:179], v[88:91]
	v_mfma_f32_16x16x32_bf16 v[76:79], v[120:123], v[184:187], v[76:79]
	v_mfma_f32_16x16x32_bf16 v[72:75], v[128:131], v[184:187], v[72:75]
	v_mfma_f32_16x16x32_bf16 v[144:147], v[124:127], v[164:167], v[144:147]
	v_mfma_f32_16x16x32_bf16 v[136:139], v[132:135], v[164:167], v[136:139]
	v_mfma_f32_16x16x32_bf16 v[108:111], v[124:127], v[172:175], v[108:111]
	v_mfma_f32_16x16x32_bf16 v[104:107], v[132:135], v[172:175], v[104:107]
	v_mfma_f32_16x16x32_bf16 v[92:95], v[124:127], v[180:183], v[92:95]
	v_mfma_f32_16x16x32_bf16 v[88:91], v[132:135], v[180:183], v[88:91]
	v_mfma_f32_16x16x32_bf16 v[76:79], v[124:127], v[188:191], v[76:79]
	v_mfma_f32_16x16x32_bf16 v[72:75], v[132:135], v[188:191], v[72:75]
	s_setprio 0
	s_setprio 1
	v_mfma_f32_16x16x32_bf16 v[116:119], v[140:143], v[160:163], v[116:119]
	v_mfma_f32_16x16x32_bf16 v[112:115], v[152:155], v[160:163], v[112:115]
	v_mfma_f32_16x16x32_bf16 v[100:103], v[140:143], v[168:171], v[100:103]
	v_mfma_f32_16x16x32_bf16 v[96:99], v[152:155], v[168:171], v[96:99]
	v_mfma_f32_16x16x32_bf16 v[84:87], v[140:143], v[176:179], v[84:87]
	v_mfma_f32_16x16x32_bf16 v[80:83], v[152:155], v[176:179], v[80:83]
	v_mfma_f32_16x16x32_bf16 v[68:71], v[140:143], v[184:187], v[68:71]
	v_mfma_f32_16x16x32_bf16 v[64:67], v[152:155], v[184:187], v[64:67]
	v_mfma_f32_16x16x32_bf16 v[116:119], v[148:151], v[164:167], v[116:119]
	v_mfma_f32_16x16x32_bf16 v[112:115], v[156:159], v[164:167], v[112:115]
	v_mfma_f32_16x16x32_bf16 v[100:103], v[148:151], v[172:175], v[100:103]
	v_mfma_f32_16x16x32_bf16 v[96:99], v[156:159], v[172:175], v[96:99]
	v_mfma_f32_16x16x32_bf16 v[84:87], v[148:151], v[180:183], v[84:87]
	v_mfma_f32_16x16x32_bf16 v[80:83], v[156:159], v[180:183], v[80:83]
	v_mfma_f32_16x16x32_bf16 v[68:71], v[148:151], v[188:191], v[68:71]
	v_mfma_f32_16x16x32_bf16 v[64:67], v[156:159], v[188:191], v[64:67]
	s_barrier
	s_setprio 0
	s_add_i32 s65, s51, s37
	s_mov_b32 m0, s65
	s_nop 0
	global_load_lds_dwordx4 v194, s[30:31]
	s_add_i32 m0, s65, 0x2000
	s_add_u32 s66, s30, 0x40000
	s_addc_u32 s67, s31, 0
	s_add_i32 s65, s60, s37
	global_load_lds_dwordx4 v198, s[30:31]
	s_mov_b32 m0, s65
	s_nop 0
	global_load_lds_dwordx4 v194, s[66:67]
	s_add_i32 m0, s65, 0x2000
	s_nop 0
	global_load_lds_dwordx4 v198, s[66:67]
	s_mov_b32 m0, s27
	s_nop 0
	global_load_lds_dwordx4 v192, s[34:35]
	s_mov_b32 m0, s38
	s_nop 0
	global_load_lds_dwordx4 v196, s[34:35]
	ds_read_b128 v[160:163], v248 offset:16384
	ds_read_b128 v[164:167], v248 offset:17408
	ds_read_b128 v[168:171], v248 offset:18432
	ds_read_b128 v[172:175], v248 offset:19456
	ds_read_b128 v[176:179], v248 offset:20480
	ds_read_b128 v[180:183], v248 offset:21504
	ds_read_b128 v[184:187], v248 offset:22528
	ds_read_b128 v[188:191], v248 offset:23552
	s_waitcnt vmcnt(8)
	s_waitcnt lgkmcnt(0)
	s_setprio 1
	s_barrier
	v_mfma_f32_16x16x32_bf16 v[60:63], v[120:123], v[160:163], v[60:63]
	v_mfma_f32_16x16x32_bf16 v[56:59], v[128:131], v[160:163], v[56:59]
	v_mfma_f32_16x16x32_bf16 v[44:47], v[120:123], v[168:171], v[44:47]
	v_mfma_f32_16x16x32_bf16 v[40:43], v[128:131], v[168:171], v[40:43]
	v_mfma_f32_16x16x32_bf16 v[28:31], v[120:123], v[176:179], v[28:31]
	v_mfma_f32_16x16x32_bf16 v[24:27], v[128:131], v[176:179], v[24:27]
	v_mfma_f32_16x16x32_bf16 v[12:15], v[120:123], v[184:187], v[12:15]
	v_mfma_f32_16x16x32_bf16 v[8:11], v[128:131], v[184:187], v[8:11]
	v_mfma_f32_16x16x32_bf16 v[60:63], v[124:127], v[164:167], v[60:63]
	v_mfma_f32_16x16x32_bf16 v[56:59], v[132:135], v[164:167], v[56:59]
	v_mfma_f32_16x16x32_bf16 v[44:47], v[124:127], v[172:175], v[44:47]
	v_mfma_f32_16x16x32_bf16 v[40:43], v[132:135], v[172:175], v[40:43]
	v_mfma_f32_16x16x32_bf16 v[28:31], v[124:127], v[180:183], v[28:31]
	v_mfma_f32_16x16x32_bf16 v[24:27], v[132:135], v[180:183], v[24:27]
	v_mfma_f32_16x16x32_bf16 v[12:15], v[124:127], v[188:191], v[12:15]
	v_mfma_f32_16x16x32_bf16 v[8:11], v[132:135], v[188:191], v[8:11]
	s_setprio 0
	s_setprio 1
	v_mfma_f32_16x16x32_bf16 v[52:55], v[140:143], v[160:163], v[52:55]
	v_mfma_f32_16x16x32_bf16 v[48:51], v[152:155], v[160:163], v[48:51]
	v_mfma_f32_16x16x32_bf16 v[36:39], v[140:143], v[168:171], v[36:39]
	v_mfma_f32_16x16x32_bf16 v[32:35], v[152:155], v[168:171], v[32:35]
	v_mfma_f32_16x16x32_bf16 v[20:23], v[140:143], v[176:179], v[20:23]
	v_mfma_f32_16x16x32_bf16 v[16:19], v[152:155], v[176:179], v[16:19]
	v_mfma_f32_16x16x32_bf16 v[4:7], v[140:143], v[184:187], v[4:7]
	v_mfma_f32_16x16x32_bf16 v[0:3], v[152:155], v[184:187], v[0:3]
	v_mfma_f32_16x16x32_bf16 v[52:55], v[148:151], v[164:167], v[52:55]
	v_mfma_f32_16x16x32_bf16 v[48:51], v[156:159], v[164:167], v[48:51]
	v_mfma_f32_16x16x32_bf16 v[36:39], v[148:151], v[172:175], v[36:39]
	v_mfma_f32_16x16x32_bf16 v[32:35], v[156:159], v[172:175], v[32:35]
	v_mfma_f32_16x16x32_bf16 v[20:23], v[148:151], v[180:183], v[20:23]
	v_mfma_f32_16x16x32_bf16 v[16:19], v[156:159], v[180:183], v[16:19]
	v_mfma_f32_16x16x32_bf16 v[4:7], v[148:151], v[188:191], v[4:7]
	v_mfma_f32_16x16x32_bf16 v[0:3], v[156:159], v[188:191], v[0:3]
	s_barrier
	s_setprio 0
	s_add_i32 s65, 0, 0x18000
	s_add_i32 s66, 0, 0x1c000
	s_add_u32 s34, s34, 0x40000
	s_addc_u32 s35, s35, 0
	s_mov_b32 m0, s39
	s_nop 0
	global_load_lds_dwordx4 v192, s[34:35]
	s_mov_b32 m0, s40
	s_nop 0
	global_load_lds_dwordx4 v196, s[34:35]
	v_add_u32_e32 v132, s65, v245
	v_add_u32_e32 v156, s66, v245
	ds_read_b128 v[120:123], v132
	ds_read_b128 v[124:127], v132 offset:1024
	ds_read_b128 v[128:131], v132 offset:2048
	ds_read_b128 v[132:135], v132 offset:3072
	ds_read_b128 v[140:143], v156
	ds_read_b128 v[148:151], v156 offset:1024
	ds_read_b128 v[152:155], v156 offset:2048
	ds_read_b128 v[156:159], v156 offset:3072
	ds_read_b128 v[160:163], v248 offset:32768
	ds_read_b128 v[164:167], v248 offset:33792
	ds_read_b128 v[168:171], v248 offset:34816
	ds_read_b128 v[172:175], v248 offset:35840
	ds_read_b128 v[176:179], v248 offset:36864
	ds_read_b128 v[180:183], v248 offset:37888
	ds_read_b128 v[184:187], v248 offset:38912
	ds_read_b128 v[188:191], v248 offset:39936
	s_waitcnt vmcnt(8)
	s_waitcnt lgkmcnt(0)
	s_setprio 1
	s_barrier
	v_mfma_f32_16x16x32_bf16 v[144:147], v[120:123], v[160:163], v[144:147]
	v_mfma_f32_16x16x32_bf16 v[136:139], v[128:131], v[160:163], v[136:139]
	v_mfma_f32_16x16x32_bf16 v[108:111], v[120:123], v[168:171], v[108:111]
	v_mfma_f32_16x16x32_bf16 v[104:107], v[128:131], v[168:171], v[104:107]
	v_mfma_f32_16x16x32_bf16 v[92:95], v[120:123], v[176:179], v[92:95]
	v_mfma_f32_16x16x32_bf16 v[88:91], v[128:131], v[176:179], v[88:91]
	v_mfma_f32_16x16x32_bf16 v[76:79], v[120:123], v[184:187], v[76:79]
	v_mfma_f32_16x16x32_bf16 v[72:75], v[128:131], v[184:187], v[72:75]
	v_mfma_f32_16x16x32_bf16 v[144:147], v[124:127], v[164:167], v[144:147]
	v_mfma_f32_16x16x32_bf16 v[136:139], v[132:135], v[164:167], v[136:139]
	v_mfma_f32_16x16x32_bf16 v[108:111], v[124:127], v[172:175], v[108:111]
	v_mfma_f32_16x16x32_bf16 v[104:107], v[132:135], v[172:175], v[104:107]
	v_mfma_f32_16x16x32_bf16 v[92:95], v[124:127], v[180:183], v[92:95]
	v_mfma_f32_16x16x32_bf16 v[88:91], v[132:135], v[180:183], v[88:91]
	v_mfma_f32_16x16x32_bf16 v[76:79], v[124:127], v[188:191], v[76:79]
	v_mfma_f32_16x16x32_bf16 v[72:75], v[132:135], v[188:191], v[72:75]
	s_setprio 0
	s_setprio 1
	v_mfma_f32_16x16x32_bf16 v[116:119], v[140:143], v[160:163], v[116:119]
	v_mfma_f32_16x16x32_bf16 v[112:115], v[152:155], v[160:163], v[112:115]
	v_mfma_f32_16x16x32_bf16 v[100:103], v[140:143], v[168:171], v[100:103]
	v_mfma_f32_16x16x32_bf16 v[96:99], v[152:155], v[168:171], v[96:99]
	v_mfma_f32_16x16x32_bf16 v[84:87], v[140:143], v[176:179], v[84:87]
	v_mfma_f32_16x16x32_bf16 v[80:83], v[152:155], v[176:179], v[80:83]
	v_mfma_f32_16x16x32_bf16 v[68:71], v[140:143], v[184:187], v[68:71]
	v_mfma_f32_16x16x32_bf16 v[64:67], v[152:155], v[184:187], v[64:67]
	v_mfma_f32_16x16x32_bf16 v[116:119], v[148:151], v[164:167], v[116:119]
	v_mfma_f32_16x16x32_bf16 v[112:115], v[156:159], v[164:167], v[112:115]
	v_mfma_f32_16x16x32_bf16 v[100:103], v[148:151], v[172:175], v[100:103]
	v_mfma_f32_16x16x32_bf16 v[96:99], v[156:159], v[172:175], v[96:99]
	v_mfma_f32_16x16x32_bf16 v[84:87], v[148:151], v[180:183], v[84:87]
	v_mfma_f32_16x16x32_bf16 v[80:83], v[156:159], v[180:183], v[80:83]
	v_mfma_f32_16x16x32_bf16 v[68:71], v[148:151], v[188:191], v[68:71]
	v_mfma_f32_16x16x32_bf16 v[64:67], v[156:159], v[188:191], v[64:67]
	s_barrier
	s_setprio 0
	s_add_i32 s34, s65, s37
	s_mov_b32 m0, s34
	s_nop 0
	global_load_lds_dwordx4 v194, s[98:99]
	s_add_i32 m0, s34, 0x2000
	s_add_u32 s30, s30, 0x40080
	s_addc_u32 s31, s31, 0
	s_add_i32 s34, s66, s37
	global_load_lds_dwordx4 v198, s[98:99]
	s_mov_b32 m0, s34
	s_nop 0
	global_load_lds_dwordx4 v194, s[30:31]
	s_add_i32 m0, s34, 0x2000
	s_nop 0
	global_load_lds_dwordx4 v198, s[30:31]
	s_mov_b32 m0, s46
	s_nop 0
	global_load_lds_dwordx4 v192, s[100:101]
	s_mov_b32 m0, s47
	s_nop 0
	global_load_lds_dwordx4 v196, s[100:101]
	ds_read_b128 v[160:163], v248 offset:49152
	ds_read_b128 v[164:167], v248 offset:50176
	ds_read_b128 v[168:171], v248 offset:51200
	ds_read_b128 v[172:175], v248 offset:52224
	ds_read_b128 v[176:179], v248 offset:53248
	ds_read_b128 v[180:183], v248 offset:54272
	ds_read_b128 v[184:187], v248 offset:55296
	ds_read_b128 v[188:191], v248 offset:56320
	s_waitcnt vmcnt(8)
	s_waitcnt lgkmcnt(0)
	s_setprio 1
	s_barrier
	v_mfma_f32_16x16x32_bf16 v[60:63], v[120:123], v[160:163], v[60:63]
	v_mfma_f32_16x16x32_bf16 v[56:59], v[128:131], v[160:163], v[56:59]
	v_mfma_f32_16x16x32_bf16 v[44:47], v[120:123], v[168:171], v[44:47]
	v_mfma_f32_16x16x32_bf16 v[40:43], v[128:131], v[168:171], v[40:43]
	v_mfma_f32_16x16x32_bf16 v[28:31], v[120:123], v[176:179], v[28:31]
	v_mfma_f32_16x16x32_bf16 v[24:27], v[128:131], v[176:179], v[24:27]
	v_mfma_f32_16x16x32_bf16 v[12:15], v[120:123], v[184:187], v[12:15]
	v_mfma_f32_16x16x32_bf16 v[8:11], v[128:131], v[184:187], v[8:11]
	v_mfma_f32_16x16x32_bf16 v[60:63], v[124:127], v[164:167], v[60:63]
	v_mfma_f32_16x16x32_bf16 v[56:59], v[132:135], v[164:167], v[56:59]
	v_mfma_f32_16x16x32_bf16 v[44:47], v[124:127], v[172:175], v[44:47]
	v_mfma_f32_16x16x32_bf16 v[40:43], v[132:135], v[172:175], v[40:43]
	v_mfma_f32_16x16x32_bf16 v[28:31], v[124:127], v[180:183], v[28:31]
	v_mfma_f32_16x16x32_bf16 v[24:27], v[132:135], v[180:183], v[24:27]
	v_mfma_f32_16x16x32_bf16 v[12:15], v[124:127], v[188:191], v[12:15]
	v_mfma_f32_16x16x32_bf16 v[8:11], v[132:135], v[188:191], v[8:11]
	s_setprio 0
	s_setprio 1
	v_mfma_f32_16x16x32_bf16 v[52:55], v[140:143], v[160:163], v[52:55]
	v_mfma_f32_16x16x32_bf16 v[48:51], v[152:155], v[160:163], v[48:51]
	v_mfma_f32_16x16x32_bf16 v[36:39], v[140:143], v[168:171], v[36:39]
	v_mfma_f32_16x16x32_bf16 v[32:35], v[152:155], v[168:171], v[32:35]
	v_mfma_f32_16x16x32_bf16 v[20:23], v[140:143], v[176:179], v[20:23]
	v_mfma_f32_16x16x32_bf16 v[16:19], v[152:155], v[176:179], v[16:19]
	v_mfma_f32_16x16x32_bf16 v[4:7], v[140:143], v[184:187], v[4:7]
	v_mfma_f32_16x16x32_bf16 v[0:3], v[152:155], v[184:187], v[0:3]
	v_mfma_f32_16x16x32_bf16 v[52:55], v[148:151], v[164:167], v[52:55]
	v_mfma_f32_16x16x32_bf16 v[48:51], v[156:159], v[164:167], v[48:51]
	v_mfma_f32_16x16x32_bf16 v[36:39], v[148:151], v[172:175], v[36:39]
	v_mfma_f32_16x16x32_bf16 v[32:35], v[156:159], v[172:175], v[32:35]
	v_mfma_f32_16x16x32_bf16 v[20:23], v[148:151], v[180:183], v[20:23]
	v_mfma_f32_16x16x32_bf16 v[16:19], v[156:159], v[180:183], v[16:19]
	v_mfma_f32_16x16x32_bf16 v[4:7], v[148:151], v[188:191], v[4:7]
	v_mfma_f32_16x16x32_bf16 v[0:3], v[156:159], v[188:191], v[0:3]
	s_barrier
	s_setprio 0
	s_add_i32 s64, s64, 2
	s_add_u32 s28, s28, 0x100
	s_addc_u32 s29, s29, 0
	s_add_u32 s62, s62, 0x100
	s_addc_u32 s63, s63, 0
	s_cmp_gt_u32 s64, 13
	s_cbranch_scc0 .LBB0_1109
	s_and_b64 vcc, exec, s[14:15]
	s_cbranch_vccz .LBB0_1112
	s_barrier

.LBB0_1193:
	s_add_u32 s30, s28, 0xfffc0080
	s_addc_u32 s31, s29, -1
	s_cmp_eq_u32 s62, 12
	s_cselect_b32 s35, s19, s31
	s_cselect_b32 s34, s50, s30
	s_cselect_b32 s31, s17, s61
	s_cselect_b32 s30, s51, s60
	s_add_u32 s98, s30, s12
	s_addc_u32 s99, s31, s13
	s_add_u32 s100, s34, s12
	s_addc_u32 s101, s35, s13
	s_add_i32 m0, s25, 0xc000
	s_nop 0
	global_load_lds_dwordx4 v136, s[28:29]
	s_add_i32 m0, s25, 0xe000
	s_nop 0
	global_load_lds_dwordx4 v138, s[28:29]
	ds_read_b128 v[154:157], v149
	ds_read_b128 v[158:161], v149 offset:1024
	ds_read_b128 v[162:165], v149 offset:2048
	ds_read_b128 v[166:169], v149 offset:3072
	ds_read_b128 v[170:173], v150
	ds_read_b128 v[174:177], v150 offset:1024
	ds_read_b128 v[178:181], v150 offset:2048
	ds_read_b128 v[182:185], v150 offset:3072
	ds_read_b128 v[186:189], v151
	ds_read_b128 v[190:193], v151 offset:1024
	ds_read_b128 v[194:197], v151 offset:2048
	ds_read_b128 v[198:201], v151 offset:3072
	ds_read_b128 v[202:205], v151 offset:4096
	ds_read_b128 v[206:209], v151 offset:5120
	ds_read_b128 v[210:213], v151 offset:6144
	ds_read_b128 v[214:217], v151 offset:7168
	s_waitcnt vmcnt(8)
	s_waitcnt lgkmcnt(0)
	s_setprio 1
	s_barrier
	v_mfma_f32_16x16x32_bf16 v[116:119], v[154:157], v[186:189], v[116:119]
	v_mfma_f32_16x16x32_bf16 v[112:115], v[162:165], v[186:189], v[112:115]
	v_mfma_f32_16x16x32_bf16 v[108:111], v[154:157], v[194:197], v[108:111]
	v_mfma_f32_16x16x32_bf16 v[100:103], v[162:165], v[194:197], v[100:103]
	v_mfma_f32_16x16x32_bf16 v[92:95], v[154:157], v[202:205], v[92:95]
	v_mfma_f32_16x16x32_bf16 v[84:87], v[162:165], v[202:205], v[84:87]
	v_mfma_f32_16x16x32_bf16 v[76:79], v[154:157], v[210:213], v[76:79]
	v_mfma_f32_16x16x32_bf16 v[68:71], v[162:165], v[210:213], v[68:71]
	v_mfma_f32_16x16x32_bf16 v[116:119], v[158:161], v[190:193], v[116:119]
	v_mfma_f32_16x16x32_bf16 v[112:115], v[166:169], v[190:193], v[112:115]
	v_mfma_f32_16x16x32_bf16 v[108:111], v[158:161], v[198:201], v[108:111]
	v_mfma_f32_16x16x32_bf16 v[100:103], v[166:169], v[198:201], v[100:103]
	v_mfma_f32_16x16x32_bf16 v[92:95], v[158:161], v[206:209], v[92:95]
	v_mfma_f32_16x16x32_bf16 v[84:87], v[166:169], v[206:209], v[84:87]
	v_mfma_f32_16x16x32_bf16 v[76:79], v[158:161], v[214:217], v[76:79]
	v_mfma_f32_16x16x32_bf16 v[68:71], v[166:169], v[214:217], v[68:71]
	s_setprio 0
	s_setprio 1
	v_mfma_f32_16x16x32_bf16 v[124:127], v[170:173], v[186:189], v[124:127]
	v_mfma_f32_16x16x32_bf16 v[120:123], v[178:181], v[186:189], v[120:123]
	v_mfma_f32_16x16x32_bf16 v[104:107], v[170:173], v[194:197], v[104:107]
	v_mfma_f32_16x16x32_bf16 v[96:99], v[178:181], v[194:197], v[96:99]
	v_mfma_f32_16x16x32_bf16 v[88:91], v[170:173], v[202:205], v[88:91]
	v_mfma_f32_16x16x32_bf16 v[80:83], v[178:181], v[202:205], v[80:83]
	v_mfma_f32_16x16x32_bf16 v[72:75], v[170:173], v[210:213], v[72:75]
	v_mfma_f32_16x16x32_bf16 v[64:67], v[178:181], v[210:213], v[64:67]
	v_mfma_f32_16x16x32_bf16 v[124:127], v[174:177], v[190:193], v[124:127]
	v_mfma_f32_16x16x32_bf16 v[120:123], v[182:185], v[190:193], v[120:123]
	v_mfma_f32_16x16x32_bf16 v[104:107], v[174:177], v[198:201], v[104:107]
	v_mfma_f32_16x16x32_bf16 v[96:99], v[182:185], v[198:201], v[96:99]
	v_mfma_f32_16x16x32_bf16 v[88:91], v[174:177], v[206:209], v[88:91]
	v_mfma_f32_16x16x32_bf16 v[80:83], v[182:185], v[206:209], v[80:83]
	v_mfma_f32_16x16x32_bf16 v[72:75], v[174:177], v[214:217], v[72:75]
	v_mfma_f32_16x16x32_bf16 v[64:67], v[182:185], v[214:217], v[64:67]
	s_barrier
	s_setprio 0
	s_add_i32 s63, s47, s5
	s_mov_b32 m0, s63
	s_nop 0
	global_load_lds_dwordx4 v132, s[30:31]
	s_add_i32 m0, s63, 0x2000
	s_add_u32 s64, s30, 0x40000
	s_addc_u32 s65, s31, 0
	s_add_i32 s63, s48, s5
	global_load_lds_dwordx4 v128, s[30:31]
	s_mov_b32 m0, s63
	s_nop 0
	global_load_lds_dwordx4 v132, s[64:65]
	s_add_i32 m0, s63, 0x2000
	s_nop 0
	global_load_lds_dwordx4 v128, s[64:65]
	s_mov_b32 m0, s25
	s_nop 0
	global_load_lds_dwordx4 v134, s[34:35]
	s_mov_b32 m0, s27
	s_nop 0
	global_load_lds_dwordx4 v130, s[34:35]
	ds_read_b128 v[186:189], v151 offset:16384
	ds_read_b128 v[190:193], v151 offset:17408
	ds_read_b128 v[194:197], v151 offset:18432
	ds_read_b128 v[198:201], v151 offset:19456
	ds_read_b128 v[202:205], v151 offset:20480
	ds_read_b128 v[206:209], v151 offset:21504
	ds_read_b128 v[210:213], v151 offset:22528
	ds_read_b128 v[214:217], v151 offset:23552
	s_waitcnt vmcnt(8)
	s_waitcnt lgkmcnt(0)
	s_setprio 1
	s_barrier
	v_mfma_f32_16x16x32_bf16 v[60:63], v[154:157], v[186:189], v[60:63]
	v_mfma_f32_16x16x32_bf16 v[52:55], v[162:165], v[186:189], v[52:55]
	v_mfma_f32_16x16x32_bf16 v[44:47], v[154:157], v[194:197], v[44:47]
	v_mfma_f32_16x16x32_bf16 v[36:39], v[162:165], v[194:197], v[36:39]
	v_mfma_f32_16x16x32_bf16 v[28:31], v[154:157], v[202:205], v[28:31]
	v_mfma_f32_16x16x32_bf16 v[20:23], v[162:165], v[202:205], v[20:23]
	v_mfma_f32_16x16x32_bf16 v[12:15], v[154:157], v[210:213], v[12:15]
	v_mfma_f32_16x16x32_bf16 v[4:7], v[162:165], v[210:213], v[4:7]
	v_mfma_f32_16x16x32_bf16 v[60:63], v[158:161], v[190:193], v[60:63]
	v_mfma_f32_16x16x32_bf16 v[52:55], v[166:169], v[190:193], v[52:55]
	v_mfma_f32_16x16x32_bf16 v[44:47], v[158:161], v[198:201], v[44:47]
	v_mfma_f32_16x16x32_bf16 v[36:39], v[166:169], v[198:201], v[36:39]
	v_mfma_f32_16x16x32_bf16 v[28:31], v[158:161], v[206:209], v[28:31]
	v_mfma_f32_16x16x32_bf16 v[20:23], v[166:169], v[206:209], v[20:23]
	v_mfma_f32_16x16x32_bf16 v[12:15], v[158:161], v[214:217], v[12:15]
	v_mfma_f32_16x16x32_bf16 v[4:7], v[166:169], v[214:217], v[4:7]
	s_setprio 0
	s_setprio 1
	v_mfma_f32_16x16x32_bf16 v[56:59], v[170:173], v[186:189], v[56:59]
	v_mfma_f32_16x16x32_bf16 v[48:51], v[178:181], v[186:189], v[48:51]
	v_mfma_f32_16x16x32_bf16 v[40:43], v[170:173], v[194:197], v[40:43]
	v_mfma_f32_16x16x32_bf16 v[32:35], v[178:181], v[194:197], v[32:35]
	v_mfma_f32_16x16x32_bf16 v[24:27], v[170:173], v[202:205], v[24:27]
	v_mfma_f32_16x16x32_bf16 v[16:19], v[178:181], v[202:205], v[16:19]
	v_mfma_f32_16x16x32_bf16 v[8:11], v[170:173], v[210:213], v[8:11]
	v_mfma_f32_16x16x32_bf16 v[0:3], v[178:181], v[210:213], v[0:3]
	v_mfma_f32_16x16x32_bf16 v[56:59], v[174:177], v[190:193], v[56:59]
	v_mfma_f32_16x16x32_bf16 v[48:51], v[182:185], v[190:193], v[48:51]
	v_mfma_f32_16x16x32_bf16 v[40:43], v[174:177], v[198:201], v[40:43]
	v_mfma_f32_16x16x32_bf16 v[32:35], v[182:185], v[198:201], v[32:35]
	v_mfma_f32_16x16x32_bf16 v[24:27], v[174:177], v[206:209], v[24:27]
	v_mfma_f32_16x16x32_bf16 v[16:19], v[182:185], v[206:209], v[16:19]
	v_mfma_f32_16x16x32_bf16 v[8:11], v[174:177], v[214:217], v[8:11]
	v_mfma_f32_16x16x32_bf16 v[0:3], v[182:185], v[214:217], v[0:3]
	s_barrier
	s_setprio 0
	s_add_i32 s63, 0, 0x18000
	s_add_i32 s64, 0, 0x1c000
	s_add_u32 s34, s34, 0x40000
	s_addc_u32 s35, s35, 0
	s_mov_b32 m0, s38
	s_nop 0
	global_load_lds_dwordx4 v134, s[34:35]
	s_mov_b32 m0, s39
	s_nop 0
	global_load_lds_dwordx4 v130, s[34:35]
	v_add_u32_e32 v153, s63, v147
	ds_read_b128 v[154:157], v153
	ds_read_b128 v[158:161], v153 offset:1024
	ds_read_b128 v[162:165], v153 offset:2048
	ds_read_b128 v[166:169], v153 offset:3072
	v_add_u32_e32 v153, s64, v147
	ds_read_b128 v[170:173], v153
	ds_read_b128 v[174:177], v153 offset:1024
	ds_read_b128 v[178:181], v153 offset:2048
	ds_read_b128 v[182:185], v153 offset:3072
	ds_read_b128 v[186:189], v151 offset:32768
	ds_read_b128 v[190:193], v151 offset:33792
	ds_read_b128 v[194:197], v151 offset:34816
	ds_read_b128 v[198:201], v151 offset:35840
	ds_read_b128 v[202:205], v151 offset:36864
	ds_read_b128 v[206:209], v151 offset:37888
	ds_read_b128 v[210:213], v151 offset:38912
	ds_read_b128 v[214:217], v151 offset:39936
	s_waitcnt vmcnt(8)
	s_waitcnt lgkmcnt(0)
	s_setprio 1
	s_barrier
	v_mfma_f32_16x16x32_bf16 v[116:119], v[154:157], v[186:189], v[116:119]
	v_mfma_f32_16x16x32_bf16 v[112:115], v[162:165], v[186:189], v[112:115]
	v_mfma_f32_16x16x32_bf16 v[108:111], v[154:157], v[194:197], v[108:111]
	v_mfma_f32_16x16x32_bf16 v[100:103], v[162:165], v[194:197], v[100:103]
	v_mfma_f32_16x16x32_bf16 v[92:95], v[154:157], v[202:205], v[92:95]
	v_mfma_f32_16x16x32_bf16 v[84:87], v[162:165], v[202:205], v[84:87]
	v_mfma_f32_16x16x32_bf16 v[76:79], v[154:157], v[210:213], v[76:79]
	v_mfma_f32_16x16x32_bf16 v[68:71], v[162:165], v[210:213], v[68:71]
	v_mfma_f32_16x16x32_bf16 v[116:119], v[158:161], v[190:193], v[116:119]
	v_mfma_f32_16x16x32_bf16 v[112:115], v[166:169], v[190:193], v[112:115]
	v_mfma_f32_16x16x32_bf16 v[108:111], v[158:161], v[198:201], v[108:111]
	v_mfma_f32_16x16x32_bf16 v[100:103], v[166:169], v[198:201], v[100:103]
	v_mfma_f32_16x16x32_bf16 v[92:95], v[158:161], v[206:209], v[92:95]
	v_mfma_f32_16x16x32_bf16 v[84:87], v[166:169], v[206:209], v[84:87]
	v_mfma_f32_16x16x32_bf16 v[76:79], v[158:161], v[214:217], v[76:79]
	v_mfma_f32_16x16x32_bf16 v[68:71], v[166:169], v[214:217], v[68:71]
	s_setprio 0
	s_setprio 1
	v_mfma_f32_16x16x32_bf16 v[124:127], v[170:173], v[186:189], v[124:127]
	v_mfma_f32_16x16x32_bf16 v[120:123], v[178:181], v[186:189], v[120:123]
	v_mfma_f32_16x16x32_bf16 v[104:107], v[170:173], v[194:197], v[104:107]
	v_mfma_f32_16x16x32_bf16 v[96:99], v[178:181], v[194:197], v[96:99]
	v_mfma_f32_16x16x32_bf16 v[88:91], v[170:173], v[202:205], v[88:91]
	v_mfma_f32_16x16x32_bf16 v[80:83], v[178:181], v[202:205], v[80:83]
	v_mfma_f32_16x16x32_bf16 v[72:75], v[170:173], v[210:213], v[72:75]
	v_mfma_f32_16x16x32_bf16 v[64:67], v[178:181], v[210:213], v[64:67]
	v_mfma_f32_16x16x32_bf16 v[124:127], v[174:177], v[190:193], v[124:127]
	v_mfma_f32_16x16x32_bf16 v[120:123], v[182:185], v[190:193], v[120:123]
	v_mfma_f32_16x16x32_bf16 v[104:107], v[174:177], v[198:201], v[104:107]
	v_mfma_f32_16x16x32_bf16 v[96:99], v[182:185], v[198:201], v[96:99]
	v_mfma_f32_16x16x32_bf16 v[88:91], v[174:177], v[206:209], v[88:91]
	v_mfma_f32_16x16x32_bf16 v[80:83], v[182:185], v[206:209], v[80:83]
	v_mfma_f32_16x16x32_bf16 v[72:75], v[174:177], v[214:217], v[72:75]
	v_mfma_f32_16x16x32_bf16 v[64:67], v[182:185], v[214:217], v[64:67]
	s_barrier
	s_setprio 0
	s_add_i32 s34, s63, s5
	s_mov_b32 m0, s34
	s_nop 0
	global_load_lds_dwordx4 v132, s[98:99]
	s_add_i32 m0, s34, 0x2000
	s_add_u32 s30, s30, 0x40080
	s_addc_u32 s31, s31, 0
	s_add_i32 s34, s64, s5
	global_load_lds_dwordx4 v128, s[98:99]
	s_mov_b32 m0, s34
	s_nop 0
	global_load_lds_dwordx4 v132, s[30:31]
	s_add_i32 m0, s34, 0x2000
	s_nop 0
	global_load_lds_dwordx4 v128, s[30:31]
	s_mov_b32 m0, s41
	s_nop 0
	global_load_lds_dwordx4 v134, s[100:101]
	s_mov_b32 m0, s42
	s_nop 0
	global_load_lds_dwordx4 v130, s[100:101]
	ds_read_b128 v[186:189], v151 offset:49152
	ds_read_b128 v[190:193], v151 offset:50176
	ds_read_b128 v[194:197], v151 offset:51200
	ds_read_b128 v[198:201], v151 offset:52224
	ds_read_b128 v[202:205], v151 offset:53248
	ds_read_b128 v[206:209], v151 offset:54272
	ds_read_b128 v[210:213], v151 offset:55296
	ds_read_b128 v[214:217], v151 offset:56320
	s_waitcnt vmcnt(8)
	s_waitcnt lgkmcnt(0)
	s_setprio 1
	s_barrier
	v_mfma_f32_16x16x32_bf16 v[60:63], v[154:157], v[186:189], v[60:63]
	v_mfma_f32_16x16x32_bf16 v[52:55], v[162:165], v[186:189], v[52:55]
	v_mfma_f32_16x16x32_bf16 v[44:47], v[154:157], v[194:197], v[44:47]
	v_mfma_f32_16x16x32_bf16 v[36:39], v[162:165], v[194:197], v[36:39]
	v_mfma_f32_16x16x32_bf16 v[28:31], v[154:157], v[202:205], v[28:31]
	v_mfma_f32_16x16x32_bf16 v[20:23], v[162:165], v[202:205], v[20:23]
	v_mfma_f32_16x16x32_bf16 v[12:15], v[154:157], v[210:213], v[12:15]
	v_mfma_f32_16x16x32_bf16 v[4:7], v[162:165], v[210:213], v[4:7]
	v_mfma_f32_16x16x32_bf16 v[60:63], v[158:161], v[190:193], v[60:63]
	v_mfma_f32_16x16x32_bf16 v[52:55], v[166:169], v[190:193], v[52:55]
	v_mfma_f32_16x16x32_bf16 v[44:47], v[158:161], v[198:201], v[44:47]
	v_mfma_f32_16x16x32_bf16 v[36:39], v[166:169], v[198:201], v[36:39]
	v_mfma_f32_16x16x32_bf16 v[28:31], v[158:161], v[206:209], v[28:31]
	v_mfma_f32_16x16x32_bf16 v[20:23], v[166:169], v[206:209], v[20:23]
	v_mfma_f32_16x16x32_bf16 v[12:15], v[158:161], v[214:217], v[12:15]
	v_mfma_f32_16x16x32_bf16 v[4:7], v[166:169], v[214:217], v[4:7]
	s_setprio 0
	s_setprio 1
	v_mfma_f32_16x16x32_bf16 v[56:59], v[170:173], v[186:189], v[56:59]
	v_mfma_f32_16x16x32_bf16 v[48:51], v[178:181], v[186:189], v[48:51]
	v_mfma_f32_16x16x32_bf16 v[40:43], v[170:173], v[194:197], v[40:43]
	v_mfma_f32_16x16x32_bf16 v[32:35], v[178:181], v[194:197], v[32:35]
	v_mfma_f32_16x16x32_bf16 v[24:27], v[170:173], v[202:205], v[24:27]
	v_mfma_f32_16x16x32_bf16 v[16:19], v[178:181], v[202:205], v[16:19]
	v_mfma_f32_16x16x32_bf16 v[8:11], v[170:173], v[210:213], v[8:11]
	v_mfma_f32_16x16x32_bf16 v[0:3], v[178:181], v[210:213], v[0:3]
	v_mfma_f32_16x16x32_bf16 v[56:59], v[174:177], v[190:193], v[56:59]
	v_mfma_f32_16x16x32_bf16 v[48:51], v[182:185], v[190:193], v[48:51]
	v_mfma_f32_16x16x32_bf16 v[40:43], v[174:177], v[198:201], v[40:43]
	v_mfma_f32_16x16x32_bf16 v[32:35], v[182:185], v[198:201], v[32:35]
	v_mfma_f32_16x16x32_bf16 v[24:27], v[174:177], v[206:209], v[24:27]
	v_mfma_f32_16x16x32_bf16 v[16:19], v[182:185], v[206:209], v[16:19]
	v_mfma_f32_16x16x32_bf16 v[8:11], v[174:177], v[214:217], v[8:11]
	v_mfma_f32_16x16x32_bf16 v[0:3], v[182:185], v[214:217], v[0:3]
	s_barrier
	s_setprio 0
	s_add_i32 s62, s62, 2
	s_add_u32 s28, s28, 0x100
	s_addc_u32 s29, s29, 0
	s_add_u32 s60, s60, 0x100
	s_addc_u32 s61, s61, 0
	s_cmp_gt_u32 s62, 13
	s_cbranch_scc0 .LBB0_1193
	s_and_b64 vcc, exec, s[14:15]
	s_cbranch_vccz .LBB0_1196
	s_barrier

.LBB0_1273:
	s_add_u32 s18, s16, 0x100
	s_addc_u32 s19, s17, 0
	s_cmp_eq_u32 s46, 40
	s_cselect_b32 s23, s5, s19
	s_cselect_b32 s22, s4, s18
	s_cselect_b32 s21, s15, s45
	s_cselect_b32 s20, s14, s44
	s_add_u32 s98, s20, s10
	s_addc_u32 s99, s21, s11
	s_add_u32 s100, s22, s10
	s_addc_u32 s101, s23, s11
	s_add_i32 m0, s26, 0xc000
	s_nop 0
	global_load_lds_dwordx4 v172, s[16:17]
	s_add_i32 m0, s26, 0xe000
	s_nop 0
	global_load_lds_dwordx4 v174, s[16:17]
	ds_read_b128 v[128:131], v197
	ds_read_b128 v[132:135], v197 offset:1024
	ds_read_b128 v[136:139], v197 offset:2048
	ds_read_b128 v[140:143], v197 offset:3072
	ds_read_b128 v[144:147], v198
	ds_read_b128 v[148:151], v198 offset:1024
	ds_read_b128 v[152:155], v198 offset:2048
	ds_read_b128 v[156:159], v198 offset:3072
	ds_read_b128 v[160:163], v199
	ds_read_b128 v[180:183], v199 offset:1024
	ds_read_b128 v[184:187], v199 offset:2048
	ds_read_b128 v[188:191], v199 offset:3072
	ds_read_b128 v[200:203], v199 offset:4096
	ds_read_b128 v[204:207], v199 offset:5120
	ds_read_b128 v[208:211], v199 offset:6144
	ds_read_b128 v[212:215], v199 offset:7168
	s_waitcnt vmcnt(8)
	s_waitcnt lgkmcnt(0)
	s_setprio 1
	s_barrier
	v_mfma_f32_16x16x32_bf16 v[124:127], v[128:131], v[160:163], v[124:127]
	v_mfma_f32_16x16x32_bf16 v[120:123], v[136:139], v[160:163], v[120:123]
	v_mfma_f32_16x16x32_bf16 v[112:115], v[128:131], v[184:187], v[112:115]
	v_mfma_f32_16x16x32_bf16 v[104:107], v[136:139], v[184:187], v[104:107]
	v_mfma_f32_16x16x32_bf16 v[96:99], v[128:131], v[200:203], v[96:99]
	v_mfma_f32_16x16x32_bf16 v[88:91], v[136:139], v[200:203], v[88:91]
	v_mfma_f32_16x16x32_bf16 v[80:83], v[128:131], v[208:211], v[80:83]
	v_mfma_f32_16x16x32_bf16 v[72:75], v[136:139], v[208:211], v[72:75]
	v_mfma_f32_16x16x32_bf16 v[124:127], v[132:135], v[180:183], v[124:127]
	v_mfma_f32_16x16x32_bf16 v[120:123], v[140:143], v[180:183], v[120:123]
	v_mfma_f32_16x16x32_bf16 v[112:115], v[132:135], v[188:191], v[112:115]
	v_mfma_f32_16x16x32_bf16 v[104:107], v[140:143], v[188:191], v[104:107]
	v_mfma_f32_16x16x32_bf16 v[96:99], v[132:135], v[204:207], v[96:99]
	v_mfma_f32_16x16x32_bf16 v[88:91], v[140:143], v[204:207], v[88:91]
	v_mfma_f32_16x16x32_bf16 v[80:83], v[132:135], v[212:215], v[80:83]
	v_mfma_f32_16x16x32_bf16 v[72:75], v[140:143], v[212:215], v[72:75]
	s_setprio 0
	s_setprio 1
	v_mfma_f32_16x16x32_bf16 v[116:119], v[144:147], v[160:163], v[116:119]
	v_mfma_f32_16x16x32_bf16 v[108:111], v[152:155], v[160:163], v[108:111]
	v_mfma_f32_16x16x32_bf16 v[100:103], v[144:147], v[184:187], v[100:103]
	v_mfma_f32_16x16x32_bf16 v[92:95], v[152:155], v[184:187], v[92:95]
	v_mfma_f32_16x16x32_bf16 v[84:87], v[144:147], v[200:203], v[84:87]
	v_mfma_f32_16x16x32_bf16 v[76:79], v[152:155], v[200:203], v[76:79]
	v_mfma_f32_16x16x32_bf16 v[68:71], v[144:147], v[208:211], v[68:71]
	v_mfma_f32_16x16x32_bf16 v[64:67], v[152:155], v[208:211], v[64:67]
	v_mfma_f32_16x16x32_bf16 v[116:119], v[148:151], v[180:183], v[116:119]
	v_mfma_f32_16x16x32_bf16 v[108:111], v[156:159], v[180:183], v[108:111]
	v_mfma_f32_16x16x32_bf16 v[100:103], v[148:151], v[188:191], v[100:103]
	v_mfma_f32_16x16x32_bf16 v[92:95], v[156:159], v[188:191], v[92:95]
	v_mfma_f32_16x16x32_bf16 v[84:87], v[148:151], v[204:207], v[84:87]
	v_mfma_f32_16x16x32_bf16 v[76:79], v[156:159], v[204:207], v[76:79]
	v_mfma_f32_16x16x32_bf16 v[68:71], v[148:151], v[212:215], v[68:71]
	v_mfma_f32_16x16x32_bf16 v[64:67], v[156:159], v[212:215], v[64:67]
	s_barrier
	s_setprio 0
	s_add_i32 s16, s38, s25
	s_mov_b32 m0, s16
	s_nop 0
	global_load_lds_dwordx4 v166, s[20:21]
	s_add_i32 m0, s16, 0x2000
	s_add_u32 s16, s20, 0xb0000
	s_addc_u32 s17, s21, 0
	s_add_i32 s47, s39, s25
	global_load_lds_dwordx4 v170, s[20:21]
	s_mov_b32 m0, s47
	s_nop 0
	global_load_lds_dwordx4 v166, s[16:17]
	s_add_i32 m0, s47, 0x2000
	s_nop 0
	global_load_lds_dwordx4 v170, s[16:17]
	s_mov_b32 m0, s26
	s_nop 0
	global_load_lds_dwordx4 v164, s[22:23]
	s_mov_b32 m0, s27
	s_nop 0
	global_load_lds_dwordx4 v168, s[22:23]
	ds_read_b128 v[160:163], v199 offset:16384
	ds_read_b128 v[180:183], v199 offset:17408
	ds_read_b128 v[184:187], v199 offset:18432
	ds_read_b128 v[188:191], v199 offset:19456
	ds_read_b128 v[200:203], v199 offset:20480
	ds_read_b128 v[204:207], v199 offset:21504
	ds_read_b128 v[208:211], v199 offset:22528
	ds_read_b128 v[212:215], v199 offset:23552
	s_waitcnt vmcnt(8)
	s_waitcnt lgkmcnt(0)
	s_setprio 1
	s_barrier
	v_mfma_f32_16x16x32_bf16 v[60:63], v[128:131], v[160:163], v[60:63]
	v_mfma_f32_16x16x32_bf16 v[56:59], v[136:139], v[160:163], v[56:59]
	v_mfma_f32_16x16x32_bf16 v[48:51], v[128:131], v[184:187], v[48:51]
	v_mfma_f32_16x16x32_bf16 v[40:43], v[136:139], v[184:187], v[40:43]
	v_mfma_f32_16x16x32_bf16 v[32:35], v[128:131], v[200:203], v[32:35]
	v_mfma_f32_16x16x32_bf16 v[24:27], v[136:139], v[200:203], v[24:27]
	v_mfma_f32_16x16x32_bf16 v[16:19], v[128:131], v[208:211], v[16:19]
	v_mfma_f32_16x16x32_bf16 v[8:11], v[136:139], v[208:211], v[8:11]
	v_mfma_f32_16x16x32_bf16 v[60:63], v[132:135], v[180:183], v[60:63]
	v_mfma_f32_16x16x32_bf16 v[56:59], v[140:143], v[180:183], v[56:59]
	v_mfma_f32_16x16x32_bf16 v[48:51], v[132:135], v[188:191], v[48:51]
	v_mfma_f32_16x16x32_bf16 v[40:43], v[140:143], v[188:191], v[40:43]
	v_mfma_f32_16x16x32_bf16 v[32:35], v[132:135], v[204:207], v[32:35]
	v_mfma_f32_16x16x32_bf16 v[24:27], v[140:143], v[204:207], v[24:27]
	v_mfma_f32_16x16x32_bf16 v[16:19], v[132:135], v[212:215], v[16:19]
	v_mfma_f32_16x16x32_bf16 v[8:11], v[140:143], v[212:215], v[8:11]
	s_setprio 0
	s_setprio 1
	v_mfma_f32_16x16x32_bf16 v[52:55], v[144:147], v[160:163], v[52:55]
	v_mfma_f32_16x16x32_bf16 v[44:47], v[152:155], v[160:163], v[44:47]
	v_mfma_f32_16x16x32_bf16 v[36:39], v[144:147], v[184:187], v[36:39]
	v_mfma_f32_16x16x32_bf16 v[28:31], v[152:155], v[184:187], v[28:31]
	v_mfma_f32_16x16x32_bf16 v[20:23], v[144:147], v[200:203], v[20:23]
	v_mfma_f32_16x16x32_bf16 v[12:15], v[152:155], v[200:203], v[12:15]
	v_mfma_f32_16x16x32_bf16 v[4:7], v[144:147], v[208:211], v[4:7]
	v_mfma_f32_16x16x32_bf16 v[0:3], v[152:155], v[208:211], v[0:3]
	v_mfma_f32_16x16x32_bf16 v[52:55], v[148:151], v[180:183], v[52:55]
	v_mfma_f32_16x16x32_bf16 v[44:47], v[156:159], v[180:183], v[44:47]
	v_mfma_f32_16x16x32_bf16 v[36:39], v[148:151], v[188:191], v[36:39]
	v_mfma_f32_16x16x32_bf16 v[28:31], v[156:159], v[188:191], v[28:31]
	v_mfma_f32_16x16x32_bf16 v[20:23], v[148:151], v[204:207], v[20:23]
	v_mfma_f32_16x16x32_bf16 v[12:15], v[156:159], v[204:207], v[12:15]
	v_mfma_f32_16x16x32_bf16 v[4:7], v[148:151], v[212:215], v[4:7]
	v_mfma_f32_16x16x32_bf16 v[0:3], v[156:159], v[212:215], v[0:3]
	s_barrier
	s_setprio 0
	s_add_i32 s47, 0, 0x18000
	s_add_i32 s48, 0, 0x1c000
	s_add_u32 s16, s22, 0xb0000
	s_addc_u32 s17, s23, 0
	s_mov_b32 m0, s28
	s_nop 0
	global_load_lds_dwordx4 v164, s[16:17]
	s_mov_b32 m0, s29
	s_nop 0
	global_load_lds_dwordx4 v168, s[16:17]
	v_add_u32_e32 v140, s47, v196
	v_add_u32_e32 v156, s48, v196
	ds_read_b128 v[128:131], v140
	ds_read_b128 v[132:135], v140 offset:1024
	ds_read_b128 v[136:139], v140 offset:2048
	ds_read_b128 v[140:143], v140 offset:3072
	ds_read_b128 v[144:147], v156
	ds_read_b128 v[148:151], v156 offset:1024
	ds_read_b128 v[152:155], v156 offset:2048
	ds_read_b128 v[156:159], v156 offset:3072
	ds_read_b128 v[160:163], v199 offset:32768
	ds_read_b128 v[180:183], v199 offset:33792
	ds_read_b128 v[184:187], v199 offset:34816
	ds_read_b128 v[188:191], v199 offset:35840
	ds_read_b128 v[200:203], v199 offset:36864
	ds_read_b128 v[204:207], v199 offset:37888
	ds_read_b128 v[208:211], v199 offset:38912
	ds_read_b128 v[212:215], v199 offset:39936
	s_waitcnt vmcnt(8)
	s_waitcnt lgkmcnt(0)
	s_setprio 1
	s_barrier
	v_mfma_f32_16x16x32_bf16 v[124:127], v[128:131], v[160:163], v[124:127]
	v_mfma_f32_16x16x32_bf16 v[120:123], v[136:139], v[160:163], v[120:123]
	v_mfma_f32_16x16x32_bf16 v[112:115], v[128:131], v[184:187], v[112:115]
	v_mfma_f32_16x16x32_bf16 v[104:107], v[136:139], v[184:187], v[104:107]
	v_mfma_f32_16x16x32_bf16 v[96:99], v[128:131], v[200:203], v[96:99]
	v_mfma_f32_16x16x32_bf16 v[88:91], v[136:139], v[200:203], v[88:91]
	v_mfma_f32_16x16x32_bf16 v[80:83], v[128:131], v[208:211], v[80:83]
	v_mfma_f32_16x16x32_bf16 v[72:75], v[136:139], v[208:211], v[72:75]
	v_mfma_f32_16x16x32_bf16 v[124:127], v[132:135], v[180:183], v[124:127]
	v_mfma_f32_16x16x32_bf16 v[120:123], v[140:143], v[180:183], v[120:123]
	v_mfma_f32_16x16x32_bf16 v[112:115], v[132:135], v[188:191], v[112:115]
	v_mfma_f32_16x16x32_bf16 v[104:107], v[140:143], v[188:191], v[104:107]
	v_mfma_f32_16x16x32_bf16 v[96:99], v[132:135], v[204:207], v[96:99]
	v_mfma_f32_16x16x32_bf16 v[88:91], v[140:143], v[204:207], v[88:91]
	v_mfma_f32_16x16x32_bf16 v[80:83], v[132:135], v[212:215], v[80:83]
	v_mfma_f32_16x16x32_bf16 v[72:75], v[140:143], v[212:215], v[72:75]
	s_setprio 0
	s_setprio 1
	v_mfma_f32_16x16x32_bf16 v[116:119], v[144:147], v[160:163], v[116:119]
	v_mfma_f32_16x16x32_bf16 v[108:111], v[152:155], v[160:163], v[108:111]
	v_mfma_f32_16x16x32_bf16 v[100:103], v[144:147], v[184:187], v[100:103]
	v_mfma_f32_16x16x32_bf16 v[92:95], v[152:155], v[184:187], v[92:95]
	v_mfma_f32_16x16x32_bf16 v[84:87], v[144:147], v[200:203], v[84:87]
	v_mfma_f32_16x16x32_bf16 v[76:79], v[152:155], v[200:203], v[76:79]
	v_mfma_f32_16x16x32_bf16 v[68:71], v[144:147], v[208:211], v[68:71]
	v_mfma_f32_16x16x32_bf16 v[64:67], v[152:155], v[208:211], v[64:67]
	v_mfma_f32_16x16x32_bf16 v[116:119], v[148:151], v[180:183], v[116:119]
	v_mfma_f32_16x16x32_bf16 v[108:111], v[156:159], v[180:183], v[108:111]
	v_mfma_f32_16x16x32_bf16 v[100:103], v[148:151], v[188:191], v[100:103]
	v_mfma_f32_16x16x32_bf16 v[92:95], v[156:159], v[188:191], v[92:95]
	v_mfma_f32_16x16x32_bf16 v[84:87], v[148:151], v[204:207], v[84:87]
	v_mfma_f32_16x16x32_bf16 v[76:79], v[156:159], v[204:207], v[76:79]
	v_mfma_f32_16x16x32_bf16 v[68:71], v[148:151], v[212:215], v[68:71]
	v_mfma_f32_16x16x32_bf16 v[64:67], v[156:159], v[212:215], v[64:67]
	s_barrier
	s_setprio 0
	s_add_i32 s16, s47, s25
	s_mov_b32 m0, s16
	s_nop 0
	global_load_lds_dwordx4 v166, s[98:99]
	s_add_i32 m0, s16, 0x2000
	s_add_u32 s16, s20, 0xb0080
	s_addc_u32 s17, s21, 0
	s_add_i32 s20, s48, s25
	global_load_lds_dwordx4 v170, s[98:99]
	s_mov_b32 m0, s20
	s_nop 0
	global_load_lds_dwordx4 v166, s[16:17]
	s_add_i32 m0, s20, 0x2000
	s_nop 0
	global_load_lds_dwordx4 v170, s[16:17]
	s_mov_b32 m0, s35
	s_nop 0
	global_load_lds_dwordx4 v164, s[100:101]
	s_mov_b32 m0, s36
	s_nop 0
	global_load_lds_dwordx4 v168, s[100:101]
	ds_read_b128 v[160:163], v199 offset:49152
	ds_read_b128 v[180:183], v199 offset:50176
	ds_read_b128 v[184:187], v199 offset:51200
	ds_read_b128 v[188:191], v199 offset:52224
	ds_read_b128 v[200:203], v199 offset:53248
	ds_read_b128 v[204:207], v199 offset:54272
	ds_read_b128 v[208:211], v199 offset:55296
	ds_read_b128 v[212:215], v199 offset:56320
	s_waitcnt vmcnt(8)
	s_waitcnt lgkmcnt(0)
	s_setprio 1
	s_barrier
	v_mfma_f32_16x16x32_bf16 v[60:63], v[128:131], v[160:163], v[60:63]
	v_mfma_f32_16x16x32_bf16 v[56:59], v[136:139], v[160:163], v[56:59]
	v_mfma_f32_16x16x32_bf16 v[48:51], v[128:131], v[184:187], v[48:51]
	v_mfma_f32_16x16x32_bf16 v[40:43], v[136:139], v[184:187], v[40:43]
	v_mfma_f32_16x16x32_bf16 v[32:35], v[128:131], v[200:203], v[32:35]
	v_mfma_f32_16x16x32_bf16 v[24:27], v[136:139], v[200:203], v[24:27]
	v_mfma_f32_16x16x32_bf16 v[16:19], v[128:131], v[208:211], v[16:19]
	v_mfma_f32_16x16x32_bf16 v[8:11], v[136:139], v[208:211], v[8:11]
	v_mfma_f32_16x16x32_bf16 v[60:63], v[132:135], v[180:183], v[60:63]
	v_mfma_f32_16x16x32_bf16 v[56:59], v[140:143], v[180:183], v[56:59]
	v_mfma_f32_16x16x32_bf16 v[48:51], v[132:135], v[188:191], v[48:51]
	v_mfma_f32_16x16x32_bf16 v[40:43], v[140:143], v[188:191], v[40:43]
	v_mfma_f32_16x16x32_bf16 v[32:35], v[132:135], v[204:207], v[32:35]
	v_mfma_f32_16x16x32_bf16 v[24:27], v[140:143], v[204:207], v[24:27]
	v_mfma_f32_16x16x32_bf16 v[16:19], v[132:135], v[212:215], v[16:19]
	v_mfma_f32_16x16x32_bf16 v[8:11], v[140:143], v[212:215], v[8:11]
	s_setprio 0
	s_setprio 1
	v_mfma_f32_16x16x32_bf16 v[52:55], v[144:147], v[160:163], v[52:55]
	v_mfma_f32_16x16x32_bf16 v[44:47], v[152:155], v[160:163], v[44:47]
	v_mfma_f32_16x16x32_bf16 v[36:39], v[144:147], v[184:187], v[36:39]
	v_mfma_f32_16x16x32_bf16 v[28:31], v[152:155], v[184:187], v[28:31]
	v_mfma_f32_16x16x32_bf16 v[20:23], v[144:147], v[200:203], v[20:23]
	v_mfma_f32_16x16x32_bf16 v[12:15], v[152:155], v[200:203], v[12:15]
	v_mfma_f32_16x16x32_bf16 v[4:7], v[144:147], v[208:211], v[4:7]
	v_mfma_f32_16x16x32_bf16 v[0:3], v[152:155], v[208:211], v[0:3]
	v_mfma_f32_16x16x32_bf16 v[52:55], v[148:151], v[180:183], v[52:55]
	v_mfma_f32_16x16x32_bf16 v[44:47], v[156:159], v[180:183], v[44:47]
	v_mfma_f32_16x16x32_bf16 v[36:39], v[148:151], v[188:191], v[36:39]
	v_mfma_f32_16x16x32_bf16 v[28:31], v[156:159], v[188:191], v[28:31]
	v_mfma_f32_16x16x32_bf16 v[20:23], v[148:151], v[204:207], v[20:23]
	v_mfma_f32_16x16x32_bf16 v[12:15], v[156:159], v[204:207], v[12:15]
	v_mfma_f32_16x16x32_bf16 v[4:7], v[148:151], v[212:215], v[4:7]
	v_mfma_f32_16x16x32_bf16 v[0:3], v[156:159], v[212:215], v[0:3]
	s_barrier
	s_setprio 0
	s_add_i32 s46, s46, 2
	s_add_u32 s44, s44, 0x100
	s_addc_u32 s45, s45, 0
	s_cmp_gt_u32 s46, 41
	s_mov_b64 s[16:17], s[18:19]
	s_cbranch_scc0 .LBB0_1273
	s_and_b64 vcc, exec, s[12:13]
	s_cbranch_vccz .LBB0_1276
	s_barrier
